# all 8-phase GEMM K-loops: the two vmcnt(6) waits per trip replaced by per-phase counted vmcnt(10) waits that cover exactly what the next phase reads from LDS (loads get 5-6 phases instead of 3 to land
# speedup vs baseline: 1.0045x; 1.0045x over previous
.LBB0_126:
	ds_read_b128 v[148:151], v145
	ds_read_b128 v[152:155], v145 offset:1024
	ds_read_b128 v[156:159], v145 offset:2048
	ds_read_b128 v[160:163], v145 offset:3072
	s_add_i32 s59, s28, 2
	s_add_u32 s30, s26, 0x80
	s_addc_u32 s29, s27, 0
	s_cmp_eq_u32 s46, s28
	s_cselect_b32 s28, s24, s30
	s_cselect_b32 s29, s25, s29
	s_cselect_b32 s31, s7, s58
	s_cselect_b32 s30, s6, s57
	v_lshl_add_u64 v[196:197], s[26:27], 0, v[140:141]
	s_add_i32 m0, s38, 0xc000
	ds_read_b128 v[164:167], v146
	ds_read_b128 v[168:171], v146 offset:1024
	ds_read_b128 v[172:175], v146 offset:2048
	ds_read_b128 v[176:179], v146 offset:3072
	ds_read_b128 v[180:183], v146 offset:4096
	ds_read_b128 v[184:187], v146 offset:5120
	ds_read_b128 v[188:191], v146 offset:6144
	ds_read_b128 v[192:195], v146 offset:7168
	global_load_lds_dwordx4 v[196:197], off
	v_lshl_add_u64 v[196:197], s[26:27], 0, v[138:139]
	s_add_i32 m0, s38, 0xe000
	s_nop 0
	global_load_lds_dwordx4 v[196:197], off
	s_waitcnt lgkmcnt(8)
	s_waitcnt vmcnt(10)
	s_barrier
	s_waitcnt lgkmcnt(0)
	s_setprio 1
	s_waitcnt lgkmcnt(0)
	v_mfma_f32_16x16x32_bf16 v[120:123], v[148:151], v[164:167], v[120:123]
	v_mfma_f32_16x16x32_bf16 v[124:127], v[156:159], v[164:167], v[124:127]
	v_mfma_f32_16x16x32_bf16 v[108:111], v[148:151], v[172:175], v[108:111]
	v_mfma_f32_16x16x32_bf16 v[104:107], v[156:159], v[172:175], v[104:107]
	v_mfma_f32_16x16x32_bf16 v[92:95], v[148:151], v[180:183], v[92:95]
	v_mfma_f32_16x16x32_bf16 v[88:91], v[156:159], v[180:183], v[88:91]
	v_mfma_f32_16x16x32_bf16 v[76:79], v[148:151], v[188:191], v[76:79]
	v_mfma_f32_16x16x32_bf16 v[72:75], v[156:159], v[188:191], v[72:75]
	v_mfma_f32_16x16x32_bf16 v[120:123], v[152:155], v[168:171], v[120:123]
	v_mfma_f32_16x16x32_bf16 v[124:127], v[160:163], v[168:171], v[124:127]
	v_mfma_f32_16x16x32_bf16 v[108:111], v[152:155], v[176:179], v[108:111]
	v_mfma_f32_16x16x32_bf16 v[104:107], v[160:163], v[176:179], v[104:107]
	v_mfma_f32_16x16x32_bf16 v[92:95], v[152:155], v[184:187], v[92:95]
	v_mfma_f32_16x16x32_bf16 v[88:91], v[160:163], v[184:187], v[88:91]
	v_mfma_f32_16x16x32_bf16 v[76:79], v[152:155], v[192:195], v[76:79]
	v_mfma_f32_16x16x32_bf16 v[72:75], v[160:163], v[192:195], v[72:75]
	s_setprio 0
	s_barrier
	s_add_i32 s60, s47, s37
	v_lshl_add_u64 v[214:215], s[30:31], 0, v[130:131]
	s_mov_b32 m0, s60
	ds_read_b128 v[196:199], v147
	ds_read_b128 v[200:203], v147 offset:1024
	ds_read_b128 v[204:207], v147 offset:2048
	ds_read_b128 v[210:213], v147 offset:3072
	global_load_lds_dwordx4 v[214:215], off
	v_lshl_add_u64 v[216:217], s[30:31], 0, v[134:135]
	s_add_i32 m0, s60, 0x2000
	s_nop 0
	global_load_lds_dwordx4 v[216:217], off
	s_waitcnt vmcnt(10)
	s_barrier
	s_waitcnt lgkmcnt(0)
	s_setprio 1
	s_waitcnt lgkmcnt(0)
	v_mfma_f32_16x16x32_bf16 v[116:119], v[196:199], v[164:167], v[116:119]
	v_mfma_f32_16x16x32_bf16 v[112:115], v[204:207], v[164:167], v[112:115]
	v_mfma_f32_16x16x32_bf16 v[100:103], v[196:199], v[172:175], v[100:103]
	v_mfma_f32_16x16x32_bf16 v[96:99], v[204:207], v[172:175], v[96:99]
	v_mfma_f32_16x16x32_bf16 v[84:87], v[196:199], v[180:183], v[84:87]
	v_mfma_f32_16x16x32_bf16 v[80:83], v[204:207], v[180:183], v[80:83]
	v_mfma_f32_16x16x32_bf16 v[68:71], v[196:199], v[188:191], v[68:71]
	v_mfma_f32_16x16x32_bf16 v[64:67], v[204:207], v[188:191], v[64:67]
	v_mfma_f32_16x16x32_bf16 v[116:119], v[200:203], v[168:171], v[116:119]
	v_mfma_f32_16x16x32_bf16 v[112:115], v[210:213], v[168:171], v[112:115]
	v_mfma_f32_16x16x32_bf16 v[100:103], v[200:203], v[176:179], v[100:103]
	v_mfma_f32_16x16x32_bf16 v[96:99], v[210:213], v[176:179], v[96:99]
	v_mfma_f32_16x16x32_bf16 v[84:87], v[200:203], v[184:187], v[84:87]
	v_mfma_f32_16x16x32_bf16 v[80:83], v[210:213], v[184:187], v[80:83]
	v_mfma_f32_16x16x32_bf16 v[68:71], v[200:203], v[192:195], v[68:71]
	v_mfma_f32_16x16x32_bf16 v[64:67], v[210:213], v[192:195], v[64:67]
	s_setprio 0
	s_mov_b32 m0, s38
	v_lshl_add_u64 v[218:219], s[28:29], 0, v[128:129]
	s_barrier
	ds_read_b128 v[164:167], v146 offset:16384
	ds_read_b128 v[168:171], v146 offset:17408
	ds_read_b128 v[172:175], v146 offset:18432
	ds_read_b128 v[176:179], v146 offset:19456
	ds_read_b128 v[180:183], v146 offset:20480
	ds_read_b128 v[184:187], v146 offset:21504
	ds_read_b128 v[188:191], v146 offset:22528
	ds_read_b128 v[192:195], v146 offset:23552
	global_load_lds_dwordx4 v[218:219], off
	v_lshl_add_u64 v[220:221], s[28:29], 0, v[132:133]
	s_mov_b32 m0, s39
	s_nop 0
	global_load_lds_dwordx4 v[220:221], off
	s_barrier
	s_waitcnt lgkmcnt(0)
	s_setprio 1
	s_waitcnt lgkmcnt(0)
	v_mfma_f32_16x16x32_bf16 v[60:63], v[148:151], v[164:167], v[60:63]
	v_mfma_f32_16x16x32_bf16 v[56:59], v[156:159], v[164:167], v[56:59]
	v_mfma_f32_16x16x32_bf16 v[44:47], v[148:151], v[172:175], v[44:47]
	v_mfma_f32_16x16x32_bf16 v[40:43], v[156:159], v[172:175], v[40:43]
	v_mfma_f32_16x16x32_bf16 v[28:31], v[148:151], v[180:183], v[28:31]
	v_mfma_f32_16x16x32_bf16 v[24:27], v[156:159], v[180:183], v[24:27]
	v_mfma_f32_16x16x32_bf16 v[12:15], v[148:151], v[188:191], v[12:15]
	v_mfma_f32_16x16x32_bf16 v[8:11], v[156:159], v[188:191], v[8:11]
	v_mfma_f32_16x16x32_bf16 v[60:63], v[152:155], v[168:171], v[60:63]
	v_mfma_f32_16x16x32_bf16 v[56:59], v[160:163], v[168:171], v[56:59]
	v_mfma_f32_16x16x32_bf16 v[44:47], v[152:155], v[176:179], v[44:47]
	v_mfma_f32_16x16x32_bf16 v[40:43], v[160:163], v[176:179], v[40:43]
	v_mfma_f32_16x16x32_bf16 v[28:31], v[152:155], v[184:187], v[28:31]
	v_mfma_f32_16x16x32_bf16 v[24:27], v[160:163], v[184:187], v[24:27]
	v_mfma_f32_16x16x32_bf16 v[12:15], v[152:155], v[192:195], v[12:15]
	v_mfma_f32_16x16x32_bf16 v[8:11], v[160:163], v[192:195], v[8:11]
	s_setprio 0
	s_barrier
	s_add_u32 s30, s30, s4
	s_addc_u32 s31, s31, s5
	s_add_i32 s60, s48, s37
	v_lshl_add_u64 v[222:223], s[30:31], 0, v[130:131]
	s_mov_b32 m0, s60
	v_lshl_add_u64 v[224:225], s[30:31], 0, v[134:135]
	global_load_lds_dwordx4 v[222:223], off
	s_add_i32 m0, s60, 0x2000
	s_nop 0
	global_load_lds_dwordx4 v[224:225], off
	s_waitcnt vmcnt(10)
	s_barrier
	s_setprio 1
	v_mfma_f32_16x16x32_bf16 v[52:55], v[196:199], v[164:167], v[52:55]
	v_mfma_f32_16x16x32_bf16 v[48:51], v[204:207], v[164:167], v[48:51]
	v_mfma_f32_16x16x32_bf16 v[36:39], v[196:199], v[172:175], v[36:39]
	v_mfma_f32_16x16x32_bf16 v[32:35], v[204:207], v[172:175], v[32:35]
	v_mfma_f32_16x16x32_bf16 v[20:23], v[196:199], v[180:183], v[20:23]
	v_mfma_f32_16x16x32_bf16 v[16:19], v[204:207], v[180:183], v[16:19]
	v_mfma_f32_16x16x32_bf16 v[4:7], v[196:199], v[188:191], v[4:7]
	v_mfma_f32_16x16x32_bf16 v[0:3], v[204:207], v[188:191], v[0:3]
	v_mfma_f32_16x16x32_bf16 v[52:55], v[200:203], v[168:171], v[52:55]
	v_mfma_f32_16x16x32_bf16 v[48:51], v[210:213], v[168:171], v[48:51]
	v_mfma_f32_16x16x32_bf16 v[36:39], v[200:203], v[176:179], v[36:39]
	v_mfma_f32_16x16x32_bf16 v[32:35], v[210:213], v[176:179], v[32:35]
	v_mfma_f32_16x16x32_bf16 v[20:23], v[200:203], v[184:187], v[20:23]
	v_mfma_f32_16x16x32_bf16 v[16:19], v[210:213], v[184:187], v[16:19]
	v_mfma_f32_16x16x32_bf16 v[4:7], v[200:203], v[192:195], v[4:7]
	v_mfma_f32_16x16x32_bf16 v[0:3], v[210:213], v[192:195], v[0:3]
	s_setprio 0
	s_add_i32 s30, 0, 0x18000
	v_add_u32_e32 v160, s30, v143
	s_barrier
	ds_read_b128 v[148:151], v160
	ds_read_b128 v[152:155], v160 offset:1024
	ds_read_b128 v[156:159], v160 offset:2048
	ds_read_b128 v[160:163], v160 offset:3072
	s_add_u32 s28, s28, s4
	s_addc_u32 s29, s29, s5
	s_mov_b32 m0, s40
	v_lshl_add_u64 v[196:197], s[28:29], 0, v[128:129]
	ds_read_b128 v[164:167], v146 offset:32768
	ds_read_b128 v[168:171], v146 offset:33792
	ds_read_b128 v[172:175], v146 offset:34816
	ds_read_b128 v[176:179], v146 offset:35840
	ds_read_b128 v[180:183], v146 offset:36864
	ds_read_b128 v[184:187], v146 offset:37888
	ds_read_b128 v[188:191], v146 offset:38912
	ds_read_b128 v[192:195], v146 offset:39936
	global_load_lds_dwordx4 v[196:197], off
	v_lshl_add_u64 v[196:197], s[28:29], 0, v[132:133]
	s_mov_b32 m0, s41
	s_nop 0
	global_load_lds_dwordx4 v[196:197], off
	s_waitcnt lgkmcnt(8)
	s_waitcnt vmcnt(10)
	s_barrier
	s_waitcnt lgkmcnt(0)
	s_setprio 1
	s_waitcnt lgkmcnt(0)
	v_mfma_f32_16x16x32_bf16 v[120:123], v[148:151], v[164:167], v[120:123]
	v_mfma_f32_16x16x32_bf16 v[124:127], v[156:159], v[164:167], v[124:127]
	v_mfma_f32_16x16x32_bf16 v[108:111], v[148:151], v[172:175], v[108:111]
	v_mfma_f32_16x16x32_bf16 v[104:107], v[156:159], v[172:175], v[104:107]
	v_mfma_f32_16x16x32_bf16 v[92:95], v[148:151], v[180:183], v[92:95]
	v_mfma_f32_16x16x32_bf16 v[88:91], v[156:159], v[180:183], v[88:91]
	v_mfma_f32_16x16x32_bf16 v[76:79], v[148:151], v[188:191], v[76:79]
	v_mfma_f32_16x16x32_bf16 v[72:75], v[156:159], v[188:191], v[72:75]
	v_mfma_f32_16x16x32_bf16 v[120:123], v[152:155], v[168:171], v[120:123]
	v_mfma_f32_16x16x32_bf16 v[124:127], v[160:163], v[168:171], v[124:127]
	v_mfma_f32_16x16x32_bf16 v[108:111], v[152:155], v[176:179], v[108:111]
	v_mfma_f32_16x16x32_bf16 v[104:107], v[160:163], v[176:179], v[104:107]
	v_mfma_f32_16x16x32_bf16 v[92:95], v[152:155], v[184:187], v[92:95]
	v_mfma_f32_16x16x32_bf16 v[88:91], v[160:163], v[184:187], v[88:91]
	v_mfma_f32_16x16x32_bf16 v[76:79], v[152:155], v[192:195], v[76:79]
	v_mfma_f32_16x16x32_bf16 v[72:75], v[160:163], v[192:195], v[72:75]
	s_setprio 0
	s_barrier
	s_add_i32 s28, 0, 0x1c000
	s_add_i32 s29, s30, s37
	v_add_u32_e32 v209, s28, v143
	v_lshl_add_u64 v[214:215], v[214:215], 0, s[10:11]
	s_mov_b32 m0, s29
	ds_read_b128 v[196:199], v209
	ds_read_b128 v[200:203], v209 offset:1024
	ds_read_b128 v[204:207], v209 offset:2048
	ds_read_b128 v[210:213], v209 offset:3072
	global_load_lds_dwordx4 v[214:215], off
	v_lshl_add_u64 v[214:215], v[216:217], 0, s[10:11]
	s_add_i32 m0, s29, 0x2000
	s_nop 0
	global_load_lds_dwordx4 v[214:215], off
	s_waitcnt vmcnt(10)
	s_barrier
	s_waitcnt lgkmcnt(0)
	s_setprio 1
	s_waitcnt lgkmcnt(0)
	v_mfma_f32_16x16x32_bf16 v[116:119], v[196:199], v[164:167], v[116:119]
	v_mfma_f32_16x16x32_bf16 v[112:115], v[204:207], v[164:167], v[112:115]
	v_mfma_f32_16x16x32_bf16 v[100:103], v[196:199], v[172:175], v[100:103]
	v_mfma_f32_16x16x32_bf16 v[96:99], v[204:207], v[172:175], v[96:99]
	v_mfma_f32_16x16x32_bf16 v[84:87], v[196:199], v[180:183], v[84:87]
	v_mfma_f32_16x16x32_bf16 v[80:83], v[204:207], v[180:183], v[80:83]
	v_mfma_f32_16x16x32_bf16 v[68:71], v[196:199], v[188:191], v[68:71]
	v_mfma_f32_16x16x32_bf16 v[64:67], v[204:207], v[188:191], v[64:67]
	v_mfma_f32_16x16x32_bf16 v[116:119], v[200:203], v[168:171], v[116:119]
	v_mfma_f32_16x16x32_bf16 v[112:115], v[210:213], v[168:171], v[112:115]
	v_mfma_f32_16x16x32_bf16 v[100:103], v[200:203], v[176:179], v[100:103]
	v_mfma_f32_16x16x32_bf16 v[96:99], v[210:213], v[176:179], v[96:99]
	v_mfma_f32_16x16x32_bf16 v[84:87], v[200:203], v[184:187], v[84:87]
	v_mfma_f32_16x16x32_bf16 v[80:83], v[210:213], v[184:187], v[80:83]
	v_mfma_f32_16x16x32_bf16 v[68:71], v[200:203], v[192:195], v[68:71]
	v_mfma_f32_16x16x32_bf16 v[64:67], v[210:213], v[192:195], v[64:67]
	s_setprio 0
	s_mov_b32 m0, s43
	v_lshl_add_u64 v[214:215], v[218:219], 0, s[10:11]
	s_barrier
	ds_read_b128 v[164:167], v146 offset:49152
	ds_read_b128 v[168:171], v146 offset:50176
	ds_read_b128 v[172:175], v146 offset:51200
	ds_read_b128 v[176:179], v146 offset:52224
	ds_read_b128 v[180:183], v146 offset:53248
	ds_read_b128 v[184:187], v146 offset:54272
	ds_read_b128 v[188:191], v146 offset:55296
	ds_read_b128 v[192:195], v146 offset:56320
	global_load_lds_dwordx4 v[214:215], off
	v_lshl_add_u64 v[214:215], v[220:221], 0, s[10:11]
	s_mov_b32 m0, s44
	s_nop 0
	global_load_lds_dwordx4 v[214:215], off
	s_barrier
	s_waitcnt lgkmcnt(0)
	s_setprio 1
	s_waitcnt lgkmcnt(0)
	v_mfma_f32_16x16x32_bf16 v[60:63], v[148:151], v[164:167], v[60:63]
	v_mfma_f32_16x16x32_bf16 v[56:59], v[156:159], v[164:167], v[56:59]
	v_mfma_f32_16x16x32_bf16 v[44:47], v[148:151], v[172:175], v[44:47]
	v_mfma_f32_16x16x32_bf16 v[40:43], v[156:159], v[172:175], v[40:43]
	v_mfma_f32_16x16x32_bf16 v[28:31], v[148:151], v[180:183], v[28:31]
	v_mfma_f32_16x16x32_bf16 v[24:27], v[156:159], v[180:183], v[24:27]
	v_mfma_f32_16x16x32_bf16 v[12:15], v[148:151], v[188:191], v[12:15]
	v_mfma_f32_16x16x32_bf16 v[8:11], v[156:159], v[188:191], v[8:11]
	v_mfma_f32_16x16x32_bf16 v[60:63], v[152:155], v[168:171], v[60:63]
	v_mfma_f32_16x16x32_bf16 v[56:59], v[160:163], v[168:171], v[56:59]
	v_mfma_f32_16x16x32_bf16 v[44:47], v[152:155], v[176:179], v[44:47]
	v_mfma_f32_16x16x32_bf16 v[40:43], v[160:163], v[176:179], v[40:43]
	v_mfma_f32_16x16x32_bf16 v[28:31], v[152:155], v[184:187], v[28:31]
	v_mfma_f32_16x16x32_bf16 v[24:27], v[160:163], v[184:187], v[24:27]
	v_mfma_f32_16x16x32_bf16 v[12:15], v[152:155], v[192:195], v[12:15]
	v_mfma_f32_16x16x32_bf16 v[8:11], v[160:163], v[192:195], v[8:11]
	s_setprio 0
	s_barrier
	s_add_i32 s28, s28, s37
	v_lshl_add_u64 v[148:149], v[222:223], 0, s[10:11]
	s_mov_b32 m0, s28
	s_nop 0
	global_load_lds_dwordx4 v[148:149], off
	v_lshl_add_u64 v[148:149], v[224:225], 0, s[10:11]
	s_add_i32 m0, s28, 0x2000
	s_nop 0
	global_load_lds_dwordx4 v[148:149], off
	s_waitcnt vmcnt(10)
	s_barrier
	s_setprio 1
	v_mfma_f32_16x16x32_bf16 v[52:55], v[196:199], v[164:167], v[52:55]
	v_mfma_f32_16x16x32_bf16 v[48:51], v[204:207], v[164:167], v[48:51]
	v_mfma_f32_16x16x32_bf16 v[36:39], v[196:199], v[172:175], v[36:39]
	v_mfma_f32_16x16x32_bf16 v[32:35], v[204:207], v[172:175], v[32:35]
	v_mfma_f32_16x16x32_bf16 v[20:23], v[196:199], v[180:183], v[20:23]
	v_mfma_f32_16x16x32_bf16 v[16:19], v[204:207], v[180:183], v[16:19]
	v_mfma_f32_16x16x32_bf16 v[4:7], v[196:199], v[188:191], v[4:7]
	v_mfma_f32_16x16x32_bf16 v[0:3], v[204:207], v[188:191], v[0:3]
	v_mfma_f32_16x16x32_bf16 v[52:55], v[200:203], v[168:171], v[52:55]
	v_mfma_f32_16x16x32_bf16 v[48:51], v[210:213], v[168:171], v[48:51]
	v_mfma_f32_16x16x32_bf16 v[36:39], v[200:203], v[176:179], v[36:39]
	v_mfma_f32_16x16x32_bf16 v[32:35], v[210:213], v[176:179], v[32:35]
	v_mfma_f32_16x16x32_bf16 v[20:23], v[200:203], v[184:187], v[20:23]
	v_mfma_f32_16x16x32_bf16 v[16:19], v[210:213], v[184:187], v[16:19]
	v_mfma_f32_16x16x32_bf16 v[4:7], v[200:203], v[192:195], v[4:7]
	v_mfma_f32_16x16x32_bf16 v[0:3], v[210:213], v[192:195], v[0:3]
	s_setprio 0
	s_add_u32 s57, s57, 0x100
	s_addc_u32 s58, s58, 0
	s_add_u32 s26, s26, 0x100
	s_addc_u32 s27, s27, 0
	s_cmp_ge_i32 s59, s45
	s_mov_b32 s28, s59
	s_barrier
	s_cbranch_scc0 .LBB0_126
	s_branch .LBB0_113

.LBB0_223:
	s_add_i32 s46, s20, 2
	s_add_u32 s22, s18, 0x80
	s_addc_u32 s21, s19, 0
	s_add_i32 s47, 0, 0x10000
	v_add_u32_e32 v164, s47, v158
	ds_read_b128 v[160:163], v164
	ds_read_b128 v[176:179], v164 offset:1024
	ds_read_b128 v[180:183], v164 offset:2048
	ds_read_b128 v[184:187], v164 offset:3072
	s_cmp_eq_u32 s38, s20
	s_cselect_b32 s20, s8, s22
	s_cselect_b32 s21, s9, s21
	s_cselect_b32 s23, s11, s45
	s_cselect_b32 s22, s10, s44
	v_lshl_add_u64 v[164:165], s[18:19], 0, v[156:157]
	s_add_i32 m0, s29, 0xc000
	ds_read_b128 v[188:191], v159
	ds_read_b128 v[192:195], v159 offset:1024
	ds_read_b128 v[196:199], v159 offset:2048
	ds_read_b128 v[200:203], v159 offset:3072
	ds_read_b128 v[204:207], v159 offset:4096
	ds_read_b128 v[218:221], v159 offset:5120
	ds_read_b128 v[224:227], v159 offset:6144
	ds_read_b128 v[228:231], v159 offset:7168
	global_load_lds_dwordx4 v[164:165], off
	v_lshl_add_u64 v[164:165], s[18:19], 0, v[154:155]
	s_add_i32 m0, s29, 0xe000
	s_nop 0
	global_load_lds_dwordx4 v[164:165], off
	s_waitcnt lgkmcnt(8)
	s_waitcnt vmcnt(10)
	s_barrier
	s_waitcnt lgkmcnt(0)
	s_setprio 1
	s_waitcnt lgkmcnt(0)
	v_mfma_f32_16x16x32_bf16 v[124:127], v[160:163], v[188:191], v[124:127]
	v_mfma_f32_16x16x32_bf16 v[128:131], v[180:183], v[188:191], v[128:131]
	v_mfma_f32_16x16x32_bf16 v[112:115], v[160:163], v[196:199], v[112:115]
	v_mfma_f32_16x16x32_bf16 v[108:111], v[180:183], v[196:199], v[108:111]
	v_mfma_f32_16x16x32_bf16 v[96:99], v[160:163], v[204:207], v[96:99]
	v_mfma_f32_16x16x32_bf16 v[92:95], v[180:183], v[204:207], v[92:95]
	v_mfma_f32_16x16x32_bf16 v[76:79], v[160:163], v[224:227], v[76:79]
	v_mfma_f32_16x16x32_bf16 v[72:75], v[180:183], v[224:227], v[72:75]
	v_mfma_f32_16x16x32_bf16 v[124:127], v[176:179], v[192:195], v[124:127]
	v_mfma_f32_16x16x32_bf16 v[128:131], v[184:187], v[192:195], v[128:131]
	v_mfma_f32_16x16x32_bf16 v[112:115], v[176:179], v[200:203], v[112:115]
	v_mfma_f32_16x16x32_bf16 v[108:111], v[184:187], v[200:203], v[108:111]
	v_mfma_f32_16x16x32_bf16 v[96:99], v[176:179], v[218:221], v[96:99]
	v_mfma_f32_16x16x32_bf16 v[92:95], v[184:187], v[218:221], v[92:95]
	v_mfma_f32_16x16x32_bf16 v[76:79], v[176:179], v[228:231], v[76:79]
	v_mfma_f32_16x16x32_bf16 v[72:75], v[184:187], v[228:231], v[72:75]
	s_setprio 0
	s_barrier
	s_add_i32 s48, 0, 0x14000
	v_add_u32_e32 v164, s48, v158
	s_add_i32 s47, s47, s28
	ds_read_b128 v[232:235], v164
	ds_read_b128 v[236:239], v164 offset:1024
	ds_read_b128 v[240:243], v164 offset:2048
	ds_read_b128 v[244:247], v164 offset:3072
	v_lshl_add_u64 v[164:165], s[22:23], 0, v[166:167]
	s_mov_b32 m0, s47
	v_lshl_add_u64 v[248:249], s[22:23], 0, v[132:133]
	global_load_lds_dwordx4 v[164:165], off
	s_add_i32 m0, s47, 0x2000
	s_nop 0
	global_load_lds_dwordx4 v[248:249], off
	s_waitcnt vmcnt(10)
	s_barrier
	s_waitcnt lgkmcnt(0)
	s_setprio 1
	s_waitcnt lgkmcnt(0)
	v_mfma_f32_16x16x32_bf16 v[120:123], v[232:235], v[188:191], v[120:123]
	v_mfma_f32_16x16x32_bf16 v[116:119], v[240:243], v[188:191], v[116:119]
	v_mfma_f32_16x16x32_bf16 v[104:107], v[232:235], v[196:199], v[104:107]
	v_mfma_f32_16x16x32_bf16 v[100:103], v[240:243], v[196:199], v[100:103]
	v_mfma_f32_16x16x32_bf16 v[88:91], v[232:235], v[204:207], v[88:91]
	v_mfma_f32_16x16x32_bf16 v[84:87], v[240:243], v[204:207], v[84:87]
	v_mfma_f32_16x16x32_bf16 v[68:71], v[232:235], v[224:227], v[68:71]
	v_mfma_f32_16x16x32_bf16 v[64:67], v[240:243], v[224:227], v[64:67]
	v_mfma_f32_16x16x32_bf16 v[120:123], v[236:239], v[192:195], v[120:123]
	v_mfma_f32_16x16x32_bf16 v[116:119], v[244:247], v[192:195], v[116:119]
	v_mfma_f32_16x16x32_bf16 v[104:107], v[236:239], v[200:203], v[104:107]
	v_mfma_f32_16x16x32_bf16 v[100:103], v[244:247], v[200:203], v[100:103]
	v_mfma_f32_16x16x32_bf16 v[88:91], v[236:239], v[218:221], v[88:91]
	v_mfma_f32_16x16x32_bf16 v[84:87], v[244:247], v[218:221], v[84:87]
	v_mfma_f32_16x16x32_bf16 v[68:71], v[236:239], v[228:231], v[68:71]
	v_mfma_f32_16x16x32_bf16 v[64:67], v[244:247], v[228:231], v[64:67]
	s_setprio 0
	s_mov_b32 m0, s29
	v_lshl_add_u64 v[250:251], s[20:21], 0, v[136:137]
	s_barrier
	ds_read_b128 v[188:191], v159 offset:16384
	ds_read_b128 v[192:195], v159 offset:17408
	ds_read_b128 v[196:199], v159 offset:18432
	ds_read_b128 v[200:203], v159 offset:19456
	ds_read_b128 v[204:207], v159 offset:20480
	ds_read_b128 v[218:221], v159 offset:21504
	ds_read_b128 v[224:227], v159 offset:22528
	ds_read_b128 v[228:231], v159 offset:23552
	global_load_lds_dwordx4 v[250:251], off
	v_lshl_add_u64 v[210:211], s[20:21], 0, v[134:135]
	s_mov_b32 m0, s30
	s_nop 0
	global_load_lds_dwordx4 v[210:211], off
	s_barrier
	s_waitcnt lgkmcnt(0)
	s_setprio 1
	s_waitcnt lgkmcnt(0)
	v_mfma_f32_16x16x32_bf16 v[60:63], v[160:163], v[188:191], v[60:63]
	v_mfma_f32_16x16x32_bf16 v[56:59], v[180:183], v[188:191], v[56:59]
	v_mfma_f32_16x16x32_bf16 v[44:47], v[160:163], v[196:199], v[44:47]
	v_mfma_f32_16x16x32_bf16 v[40:43], v[180:183], v[196:199], v[40:43]
	v_mfma_f32_16x16x32_bf16 v[28:31], v[160:163], v[204:207], v[28:31]
	v_mfma_f32_16x16x32_bf16 v[24:27], v[180:183], v[204:207], v[24:27]
	v_mfma_f32_16x16x32_bf16 v[12:15], v[160:163], v[224:227], v[12:15]
	v_mfma_f32_16x16x32_bf16 v[8:11], v[180:183], v[224:227], v[8:11]
	v_mfma_f32_16x16x32_bf16 v[60:63], v[176:179], v[192:195], v[60:63]
	v_mfma_f32_16x16x32_bf16 v[56:59], v[184:187], v[192:195], v[56:59]
	v_mfma_f32_16x16x32_bf16 v[44:47], v[176:179], v[200:203], v[44:47]
	v_mfma_f32_16x16x32_bf16 v[40:43], v[184:187], v[200:203], v[40:43]
	v_mfma_f32_16x16x32_bf16 v[28:31], v[176:179], v[218:221], v[28:31]
	v_mfma_f32_16x16x32_bf16 v[24:27], v[184:187], v[218:221], v[24:27]
	v_mfma_f32_16x16x32_bf16 v[12:15], v[176:179], v[228:231], v[12:15]
	v_mfma_f32_16x16x32_bf16 v[8:11], v[184:187], v[228:231], v[8:11]
	s_setprio 0
	s_barrier
	s_add_u32 s22, s22, s12
	s_addc_u32 s23, s23, s13
	s_add_i32 s47, s48, s28
	v_lshl_add_u64 v[170:171], s[22:23], 0, v[166:167]
	s_mov_b32 m0, s47
	v_lshl_add_u64 v[172:173], s[22:23], 0, v[132:133]
	global_load_lds_dwordx4 v[170:171], off
	s_add_i32 m0, s47, 0x2000
	s_nop 0
	global_load_lds_dwordx4 v[172:173], off
	s_waitcnt vmcnt(10)
	s_barrier
	s_setprio 1
	v_mfma_f32_16x16x32_bf16 v[52:55], v[232:235], v[188:191], v[52:55]
	v_mfma_f32_16x16x32_bf16 v[48:51], v[240:243], v[188:191], v[48:51]
	v_mfma_f32_16x16x32_bf16 v[36:39], v[232:235], v[196:199], v[36:39]
	v_mfma_f32_16x16x32_bf16 v[32:35], v[240:243], v[196:199], v[32:35]
	v_mfma_f32_16x16x32_bf16 v[20:23], v[232:235], v[204:207], v[20:23]
	v_mfma_f32_16x16x32_bf16 v[16:19], v[240:243], v[204:207], v[16:19]
	v_mfma_f32_16x16x32_bf16 v[4:7], v[232:235], v[224:227], v[4:7]
	v_mfma_f32_16x16x32_bf16 v[0:3], v[240:243], v[224:227], v[0:3]
	v_mfma_f32_16x16x32_bf16 v[52:55], v[236:239], v[192:195], v[52:55]
	v_mfma_f32_16x16x32_bf16 v[48:51], v[244:247], v[192:195], v[48:51]
	v_mfma_f32_16x16x32_bf16 v[36:39], v[236:239], v[200:203], v[36:39]
	v_mfma_f32_16x16x32_bf16 v[32:35], v[244:247], v[200:203], v[32:35]
	v_mfma_f32_16x16x32_bf16 v[20:23], v[236:239], v[218:221], v[20:23]
	v_mfma_f32_16x16x32_bf16 v[16:19], v[244:247], v[218:221], v[16:19]
	v_mfma_f32_16x16x32_bf16 v[4:7], v[236:239], v[228:231], v[4:7]
	v_mfma_f32_16x16x32_bf16 v[0:3], v[244:247], v[228:231], v[0:3]
	s_setprio 0
	s_add_i32 s22, 0, 0x18000
	v_add_u32_e32 v169, s22, v158
	s_barrier
	ds_read_b128 v[160:163], v169
	ds_read_b128 v[176:179], v169 offset:1024
	ds_read_b128 v[180:183], v169 offset:2048
	ds_read_b128 v[184:187], v169 offset:3072
	s_add_u32 s20, s20, s12
	s_addc_u32 s21, s21, s13
	s_mov_b32 m0, s31
	v_lshl_add_u64 v[232:233], s[20:21], 0, v[136:137]
	ds_read_b128 v[188:191], v159 offset:32768
	ds_read_b128 v[192:195], v159 offset:33792
	ds_read_b128 v[196:199], v159 offset:34816
	ds_read_b128 v[200:203], v159 offset:35840
	ds_read_b128 v[204:207], v159 offset:36864
	ds_read_b128 v[218:221], v159 offset:37888
	ds_read_b128 v[224:227], v159 offset:38912
	ds_read_b128 v[228:231], v159 offset:39936
	global_load_lds_dwordx4 v[232:233], off
	v_lshl_add_u64 v[232:233], s[20:21], 0, v[134:135]
	s_mov_b32 m0, s34
	s_nop 0
	global_load_lds_dwordx4 v[232:233], off
	s_waitcnt lgkmcnt(8)
	s_waitcnt vmcnt(10)
	s_barrier
	s_waitcnt lgkmcnt(0)
	s_setprio 1
	s_waitcnt lgkmcnt(0)
	v_mfma_f32_16x16x32_bf16 v[124:127], v[160:163], v[188:191], v[124:127]
	v_mfma_f32_16x16x32_bf16 v[128:131], v[180:183], v[188:191], v[128:131]
	v_mfma_f32_16x16x32_bf16 v[112:115], v[160:163], v[196:199], v[112:115]
	v_mfma_f32_16x16x32_bf16 v[108:111], v[180:183], v[196:199], v[108:111]
	v_mfma_f32_16x16x32_bf16 v[96:99], v[160:163], v[204:207], v[96:99]
	v_mfma_f32_16x16x32_bf16 v[92:95], v[180:183], v[204:207], v[92:95]
	v_mfma_f32_16x16x32_bf16 v[76:79], v[160:163], v[224:227], v[76:79]
	v_mfma_f32_16x16x32_bf16 v[72:75], v[180:183], v[224:227], v[72:75]
	v_mfma_f32_16x16x32_bf16 v[124:127], v[176:179], v[192:195], v[124:127]
	v_mfma_f32_16x16x32_bf16 v[128:131], v[184:187], v[192:195], v[128:131]
	v_mfma_f32_16x16x32_bf16 v[112:115], v[176:179], v[200:203], v[112:115]
	v_mfma_f32_16x16x32_bf16 v[108:111], v[184:187], v[200:203], v[108:111]
	v_mfma_f32_16x16x32_bf16 v[96:99], v[176:179], v[218:221], v[96:99]
	v_mfma_f32_16x16x32_bf16 v[92:95], v[184:187], v[218:221], v[92:95]
	v_mfma_f32_16x16x32_bf16 v[76:79], v[176:179], v[228:231], v[76:79]
	v_mfma_f32_16x16x32_bf16 v[72:75], v[184:187], v[228:231], v[72:75]
	s_setprio 0
	s_barrier
	s_add_i32 s20, 0, 0x1c000
	s_add_i32 s21, s22, s28
	v_add_u32_e32 v169, s20, v158
	v_lshl_add_u64 v[164:165], v[164:165], 0, s[88:89]
	s_mov_b32 m0, s21
	ds_read_b128 v[232:235], v169
	ds_read_b128 v[236:239], v169 offset:1024
	ds_read_b128 v[240:243], v169 offset:2048
	ds_read_b128 v[244:247], v169 offset:3072
	global_load_lds_dwordx4 v[164:165], off
	v_lshl_add_u64 v[164:165], v[248:249], 0, s[88:89]
	s_add_i32 m0, s21, 0x2000
	s_nop 0
	global_load_lds_dwordx4 v[164:165], off
	s_waitcnt vmcnt(10)
	s_barrier
	s_waitcnt lgkmcnt(0)
	s_setprio 1
	s_waitcnt lgkmcnt(0)
	v_mfma_f32_16x16x32_bf16 v[120:123], v[232:235], v[188:191], v[120:123]
	v_mfma_f32_16x16x32_bf16 v[116:119], v[240:243], v[188:191], v[116:119]
	v_mfma_f32_16x16x32_bf16 v[104:107], v[232:235], v[196:199], v[104:107]
	v_mfma_f32_16x16x32_bf16 v[100:103], v[240:243], v[196:199], v[100:103]
	v_mfma_f32_16x16x32_bf16 v[88:91], v[232:235], v[204:207], v[88:91]
	v_mfma_f32_16x16x32_bf16 v[84:87], v[240:243], v[204:207], v[84:87]
	v_mfma_f32_16x16x32_bf16 v[68:71], v[232:235], v[224:227], v[68:71]
	v_mfma_f32_16x16x32_bf16 v[64:67], v[240:243], v[224:227], v[64:67]
	v_mfma_f32_16x16x32_bf16 v[120:123], v[236:239], v[192:195], v[120:123]
	v_mfma_f32_16x16x32_bf16 v[116:119], v[244:247], v[192:195], v[116:119]
	v_mfma_f32_16x16x32_bf16 v[104:107], v[236:239], v[200:203], v[104:107]
	v_mfma_f32_16x16x32_bf16 v[100:103], v[244:247], v[200:203], v[100:103]
	v_mfma_f32_16x16x32_bf16 v[88:91], v[236:239], v[218:221], v[88:91]
	v_mfma_f32_16x16x32_bf16 v[84:87], v[244:247], v[218:221], v[84:87]
	v_mfma_f32_16x16x32_bf16 v[68:71], v[236:239], v[228:231], v[68:71]
	v_mfma_f32_16x16x32_bf16 v[64:67], v[244:247], v[228:231], v[64:67]
	s_setprio 0
	s_mov_b32 m0, s36
	v_lshl_add_u64 v[164:165], v[250:251], 0, s[88:89]
	s_barrier
	ds_read_b128 v[188:191], v159 offset:49152
	ds_read_b128 v[192:195], v159 offset:50176
	ds_read_b128 v[196:199], v159 offset:51200
	ds_read_b128 v[200:203], v159 offset:52224
	ds_read_b128 v[204:207], v159 offset:53248
	ds_read_b128 v[218:221], v159 offset:54272
	ds_read_b128 v[224:227], v159 offset:55296
	ds_read_b128 v[228:231], v159 offset:56320
	global_load_lds_dwordx4 v[164:165], off
	v_lshl_add_u64 v[164:165], v[210:211], 0, s[88:89]
	s_mov_b32 m0, s37
	s_nop 0
	global_load_lds_dwordx4 v[164:165], off
	s_barrier
	s_waitcnt lgkmcnt(0)
	s_setprio 1
	s_waitcnt lgkmcnt(0)
	v_mfma_f32_16x16x32_bf16 v[60:63], v[160:163], v[188:191], v[60:63]
	v_mfma_f32_16x16x32_bf16 v[56:59], v[180:183], v[188:191], v[56:59]
	v_mfma_f32_16x16x32_bf16 v[44:47], v[160:163], v[196:199], v[44:47]
	v_mfma_f32_16x16x32_bf16 v[40:43], v[180:183], v[196:199], v[40:43]
	v_mfma_f32_16x16x32_bf16 v[28:31], v[160:163], v[204:207], v[28:31]
	v_mfma_f32_16x16x32_bf16 v[24:27], v[180:183], v[204:207], v[24:27]
	v_mfma_f32_16x16x32_bf16 v[12:15], v[160:163], v[224:227], v[12:15]
	v_mfma_f32_16x16x32_bf16 v[8:11], v[180:183], v[224:227], v[8:11]
	v_mfma_f32_16x16x32_bf16 v[60:63], v[176:179], v[192:195], v[60:63]
	v_mfma_f32_16x16x32_bf16 v[56:59], v[184:187], v[192:195], v[56:59]
	v_mfma_f32_16x16x32_bf16 v[44:47], v[176:179], v[200:203], v[44:47]
	v_mfma_f32_16x16x32_bf16 v[40:43], v[184:187], v[200:203], v[40:43]
	v_mfma_f32_16x16x32_bf16 v[28:31], v[176:179], v[218:221], v[28:31]
	v_mfma_f32_16x16x32_bf16 v[24:27], v[184:187], v[218:221], v[24:27]
	v_mfma_f32_16x16x32_bf16 v[12:15], v[176:179], v[228:231], v[12:15]
	v_mfma_f32_16x16x32_bf16 v[8:11], v[184:187], v[228:231], v[8:11]
	s_setprio 0
	s_barrier
	s_add_i32 s20, s20, s28
	v_lshl_add_u64 v[160:161], v[170:171], 0, s[88:89]
	s_mov_b32 m0, s20
	s_nop 0
	global_load_lds_dwordx4 v[160:161], off
	v_lshl_add_u64 v[160:161], v[172:173], 0, s[88:89]
	s_add_i32 m0, s20, 0x2000
	s_nop 0
	global_load_lds_dwordx4 v[160:161], off
	s_waitcnt vmcnt(10)
	s_barrier
	s_setprio 1
	v_mfma_f32_16x16x32_bf16 v[52:55], v[232:235], v[188:191], v[52:55]
	v_mfma_f32_16x16x32_bf16 v[48:51], v[240:243], v[188:191], v[48:51]
	v_mfma_f32_16x16x32_bf16 v[36:39], v[232:235], v[196:199], v[36:39]
	v_mfma_f32_16x16x32_bf16 v[32:35], v[240:243], v[196:199], v[32:35]
	v_mfma_f32_16x16x32_bf16 v[20:23], v[232:235], v[204:207], v[20:23]
	v_mfma_f32_16x16x32_bf16 v[16:19], v[240:243], v[204:207], v[16:19]
	v_mfma_f32_16x16x32_bf16 v[4:7], v[232:235], v[224:227], v[4:7]
	v_mfma_f32_16x16x32_bf16 v[0:3], v[240:243], v[224:227], v[0:3]
	v_mfma_f32_16x16x32_bf16 v[52:55], v[236:239], v[192:195], v[52:55]
	v_mfma_f32_16x16x32_bf16 v[48:51], v[244:247], v[192:195], v[48:51]
	v_mfma_f32_16x16x32_bf16 v[36:39], v[236:239], v[200:203], v[36:39]
	v_mfma_f32_16x16x32_bf16 v[32:35], v[244:247], v[200:203], v[32:35]
	v_mfma_f32_16x16x32_bf16 v[20:23], v[236:239], v[218:221], v[20:23]
	v_mfma_f32_16x16x32_bf16 v[16:19], v[244:247], v[218:221], v[16:19]
	v_mfma_f32_16x16x32_bf16 v[4:7], v[236:239], v[228:231], v[4:7]
	v_mfma_f32_16x16x32_bf16 v[0:3], v[244:247], v[228:231], v[0:3]
	s_setprio 0
	s_add_u32 s44, s44, 0x100
	s_addc_u32 s45, s45, 0
	s_add_u32 s18, s18, 0x100
	s_addc_u32 s19, s19, 0
	s_cmp_ge_i32 s46, s38
	s_mov_b32 s20, s46
	s_barrier
	s_cbranch_scc0 .LBB0_223
.Lp2_last:
	s_mul_i32 s49, s43, 49
	s_add_i32 s49, s49, s42
	s_lshl_b32 s49, s49, 17
	s_add_u32 s98, s60, 0x74c2800
	s_addc_u32 s99, s61, 0
	s_add_u32 s98, s98, s49
	s_addc_u32 s99, s99, 0
	s_add_i32 s46, s20, 2
	s_add_u32 s22, s18, 0x80
	s_addc_u32 s21, s19, 0
	s_add_i32 s47, 0, 0x10000
	v_add_u32_e32 v164, s47, v158
	ds_read_b128 v[160:163], v164
	ds_read_b128 v[176:179], v164 offset:1024
	ds_read_b128 v[180:183], v164 offset:2048
	ds_read_b128 v[184:187], v164 offset:3072
	s_cmp_eq_u32 s38, s20
	s_cselect_b32 s20, s8, s22
	s_cselect_b32 s21, s9, s21
	s_cselect_b32 s23, s11, s45
	s_cselect_b32 s22, s10, s44
	v_lshl_add_u64 v[164:165], s[18:19], 0, v[156:157]
	s_add_i32 m0, s29, 0xc000
	ds_read_b128 v[188:191], v159
	ds_read_b128 v[192:195], v159 offset:1024
	ds_read_b128 v[196:199], v159 offset:2048
	ds_read_b128 v[200:203], v159 offset:3072
	ds_read_b128 v[204:207], v159 offset:4096
	ds_read_b128 v[218:221], v159 offset:5120
	ds_read_b128 v[224:227], v159 offset:6144
	ds_read_b128 v[228:231], v159 offset:7168
	global_load_lds_dwordx4 v[164:165], off
	v_lshl_add_u64 v[164:165], s[18:19], 0, v[154:155]
	s_add_i32 m0, s29, 0xe000
	s_nop 0
	global_load_lds_dwordx4 v[164:165], off
	s_waitcnt lgkmcnt(8)
	s_waitcnt vmcnt(10)
	s_barrier
	s_waitcnt lgkmcnt(0)
	s_setprio 1
	s_waitcnt lgkmcnt(0)
	v_mfma_f32_16x16x32_bf16 v[124:127], v[160:163], v[188:191], v[124:127]
	v_mfma_f32_16x16x32_bf16 v[128:131], v[180:183], v[188:191], v[128:131]
	v_mfma_f32_16x16x32_bf16 v[112:115], v[160:163], v[196:199], v[112:115]
	v_mfma_f32_16x16x32_bf16 v[108:111], v[180:183], v[196:199], v[108:111]
	v_mfma_f32_16x16x32_bf16 v[96:99], v[160:163], v[204:207], v[96:99]
	v_mfma_f32_16x16x32_bf16 v[92:95], v[180:183], v[204:207], v[92:95]
	v_mfma_f32_16x16x32_bf16 v[76:79], v[160:163], v[224:227], v[76:79]
	v_mfma_f32_16x16x32_bf16 v[72:75], v[180:183], v[224:227], v[72:75]
	v_mfma_f32_16x16x32_bf16 v[124:127], v[176:179], v[192:195], v[124:127]
	v_mfma_f32_16x16x32_bf16 v[128:131], v[184:187], v[192:195], v[128:131]
	v_mfma_f32_16x16x32_bf16 v[112:115], v[176:179], v[200:203], v[112:115]
	v_mfma_f32_16x16x32_bf16 v[108:111], v[184:187], v[200:203], v[108:111]
	v_mfma_f32_16x16x32_bf16 v[96:99], v[176:179], v[218:221], v[96:99]
	v_mfma_f32_16x16x32_bf16 v[92:95], v[184:187], v[218:221], v[92:95]
	v_mfma_f32_16x16x32_bf16 v[76:79], v[176:179], v[228:231], v[76:79]
	v_mfma_f32_16x16x32_bf16 v[72:75], v[184:187], v[228:231], v[72:75]
	s_setprio 0
	s_barrier
	s_add_i32 s48, 0, 0x14000
	v_add_u32_e32 v164, s48, v158
	s_add_i32 s47, s47, s28
	ds_read_b128 v[232:235], v164
	ds_read_b128 v[236:239], v164 offset:1024
	ds_read_b128 v[240:243], v164 offset:2048
	ds_read_b128 v[244:247], v164 offset:3072
	v_lshl_add_u64 v[164:165], s[22:23], 0, v[166:167]
	s_mov_b32 m0, s47
	v_lshl_add_u64 v[248:249], s[22:23], 0, v[132:133]
	global_load_lds_dwordx4 v[164:165], off
	s_add_i32 m0, s47, 0x2000
	s_nop 0
	global_load_lds_dwordx4 v[248:249], off
	s_waitcnt vmcnt(10)
	s_barrier
	s_waitcnt lgkmcnt(0)
	s_setprio 1
	s_waitcnt lgkmcnt(0)
	v_mfma_f32_16x16x32_bf16 v[120:123], v[232:235], v[188:191], v[120:123]
	v_mfma_f32_16x16x32_bf16 v[116:119], v[240:243], v[188:191], v[116:119]
	v_mfma_f32_16x16x32_bf16 v[104:107], v[232:235], v[196:199], v[104:107]
	v_mfma_f32_16x16x32_bf16 v[100:103], v[240:243], v[196:199], v[100:103]
	v_mfma_f32_16x16x32_bf16 v[88:91], v[232:235], v[204:207], v[88:91]
	v_mfma_f32_16x16x32_bf16 v[84:87], v[240:243], v[204:207], v[84:87]
	v_mfma_f32_16x16x32_bf16 v[68:71], v[232:235], v[224:227], v[68:71]
	v_mfma_f32_16x16x32_bf16 v[64:67], v[240:243], v[224:227], v[64:67]
	v_mfma_f32_16x16x32_bf16 v[120:123], v[236:239], v[192:195], v[120:123]
	v_mfma_f32_16x16x32_bf16 v[116:119], v[244:247], v[192:195], v[116:119]
	v_mfma_f32_16x16x32_bf16 v[104:107], v[236:239], v[200:203], v[104:107]
	v_mfma_f32_16x16x32_bf16 v[100:103], v[244:247], v[200:203], v[100:103]
	v_mfma_f32_16x16x32_bf16 v[88:91], v[236:239], v[218:221], v[88:91]
	v_mfma_f32_16x16x32_bf16 v[84:87], v[244:247], v[218:221], v[84:87]
	v_mfma_f32_16x16x32_bf16 v[68:71], v[236:239], v[228:231], v[68:71]
	v_mfma_f32_16x16x32_bf16 v[64:67], v[244:247], v[228:231], v[64:67]
	s_setprio 0
	s_mov_b32 m0, s29
	v_lshl_add_u64 v[250:251], s[20:21], 0, v[136:137]
	s_barrier
	ds_read_b128 v[188:191], v159 offset:16384
	ds_read_b128 v[192:195], v159 offset:17408
	ds_read_b128 v[196:199], v159 offset:18432
	ds_read_b128 v[200:203], v159 offset:19456
	ds_read_b128 v[204:207], v159 offset:20480
	ds_read_b128 v[218:221], v159 offset:21504
	ds_read_b128 v[224:227], v159 offset:22528
	ds_read_b128 v[228:231], v159 offset:23552
	global_load_lds_dwordx4 v[250:251], off
	v_lshl_add_u64 v[210:211], s[20:21], 0, v[134:135]
	s_mov_b32 m0, s30
	s_nop 0
	global_load_lds_dwordx4 v[210:211], off
	s_barrier
	s_waitcnt lgkmcnt(0)
	s_setprio 1
	s_waitcnt lgkmcnt(0)
	v_mfma_f32_16x16x32_bf16 v[60:63], v[160:163], v[188:191], v[60:63]
	v_mfma_f32_16x16x32_bf16 v[56:59], v[180:183], v[188:191], v[56:59]
	v_mfma_f32_16x16x32_bf16 v[44:47], v[160:163], v[196:199], v[44:47]
	v_mfma_f32_16x16x32_bf16 v[40:43], v[180:183], v[196:199], v[40:43]
	v_mfma_f32_16x16x32_bf16 v[28:31], v[160:163], v[204:207], v[28:31]
	v_mfma_f32_16x16x32_bf16 v[24:27], v[180:183], v[204:207], v[24:27]
	v_mfma_f32_16x16x32_bf16 v[12:15], v[160:163], v[224:227], v[12:15]
	v_mfma_f32_16x16x32_bf16 v[8:11], v[180:183], v[224:227], v[8:11]
	v_mfma_f32_16x16x32_bf16 v[60:63], v[176:179], v[192:195], v[60:63]
	v_mfma_f32_16x16x32_bf16 v[56:59], v[184:187], v[192:195], v[56:59]
	v_mfma_f32_16x16x32_bf16 v[44:47], v[176:179], v[200:203], v[44:47]
	v_mfma_f32_16x16x32_bf16 v[40:43], v[184:187], v[200:203], v[40:43]
	v_mfma_f32_16x16x32_bf16 v[28:31], v[176:179], v[218:221], v[28:31]
	v_mfma_f32_16x16x32_bf16 v[24:27], v[184:187], v[218:221], v[24:27]
	v_mfma_f32_16x16x32_bf16 v[12:15], v[176:179], v[228:231], v[12:15]
	v_mfma_f32_16x16x32_bf16 v[8:11], v[184:187], v[228:231], v[8:11]
	s_setprio 0
	s_barrier
	s_add_u32 s22, s22, s12
	s_addc_u32 s23, s23, s13
	s_add_i32 s47, s48, s28
	v_lshl_add_u64 v[170:171], s[22:23], 0, v[166:167]
	s_mov_b32 m0, s47
	v_lshl_add_u64 v[172:173], s[22:23], 0, v[132:133]
	global_load_lds_dwordx4 v[170:171], off
	s_add_i32 m0, s47, 0x2000
	s_nop 0
	global_load_lds_dwordx4 v[172:173], off
	s_waitcnt vmcnt(10)
	s_barrier
	s_setprio 1
	v_mfma_f32_16x16x32_bf16 v[52:55], v[232:235], v[188:191], v[52:55]
	v_mfma_f32_16x16x32_bf16 v[48:51], v[240:243], v[188:191], v[48:51]
	v_mfma_f32_16x16x32_bf16 v[36:39], v[232:235], v[196:199], v[36:39]
	v_mfma_f32_16x16x32_bf16 v[32:35], v[240:243], v[196:199], v[32:35]
	v_mfma_f32_16x16x32_bf16 v[20:23], v[232:235], v[204:207], v[20:23]
	v_mfma_f32_16x16x32_bf16 v[16:19], v[240:243], v[204:207], v[16:19]
	v_mfma_f32_16x16x32_bf16 v[4:7], v[232:235], v[224:227], v[4:7]
	v_mfma_f32_16x16x32_bf16 v[0:3], v[240:243], v[224:227], v[0:3]
	v_mfma_f32_16x16x32_bf16 v[52:55], v[236:239], v[192:195], v[52:55]
	v_mfma_f32_16x16x32_bf16 v[48:51], v[244:247], v[192:195], v[48:51]
	v_mfma_f32_16x16x32_bf16 v[36:39], v[236:239], v[200:203], v[36:39]
	v_mfma_f32_16x16x32_bf16 v[32:35], v[244:247], v[200:203], v[32:35]
	v_mfma_f32_16x16x32_bf16 v[20:23], v[236:239], v[218:221], v[20:23]
	v_mfma_f32_16x16x32_bf16 v[16:19], v[244:247], v[218:221], v[16:19]
	v_mfma_f32_16x16x32_bf16 v[4:7], v[236:239], v[228:231], v[4:7]
	v_mfma_f32_16x16x32_bf16 v[0:3], v[244:247], v[228:231], v[0:3]
	s_setprio 0
	s_add_i32 s22, 0, 0x18000
	v_add_u32_e32 v169, s22, v158
	s_barrier
	ds_read_b128 v[160:163], v169
	ds_read_b128 v[176:179], v169 offset:1024
	ds_read_b128 v[180:183], v169 offset:2048
	ds_read_b128 v[184:187], v169 offset:3072
	s_add_u32 s20, s20, s12
	s_addc_u32 s21, s21, s13
	s_mov_b32 m0, s31
	v_lshl_add_u64 v[232:233], s[20:21], 0, v[136:137]
	ds_read_b128 v[188:191], v159 offset:32768
	ds_read_b128 v[192:195], v159 offset:33792
	ds_read_b128 v[196:199], v159 offset:34816
	ds_read_b128 v[200:203], v159 offset:35840
	ds_read_b128 v[204:207], v159 offset:36864
	ds_read_b128 v[218:221], v159 offset:37888
	ds_read_b128 v[224:227], v159 offset:38912
	ds_read_b128 v[228:231], v159 offset:39936
	global_load_lds_dwordx4 v[232:233], off
	v_lshl_add_u64 v[232:233], s[20:21], 0, v[134:135]
	s_mov_b32 m0, s34
	s_nop 0
	global_load_lds_dwordx4 v[232:233], off
	s_waitcnt lgkmcnt(8)
	s_waitcnt vmcnt(10)
	s_barrier
	s_waitcnt lgkmcnt(0)
	s_setprio 1
	s_waitcnt lgkmcnt(0)
	v_mfma_f32_16x16x32_bf16 v[124:127], v[160:163], v[188:191], v[124:127]
	v_mfma_f32_16x16x32_bf16 v[128:131], v[180:183], v[188:191], v[128:131]
	v_mfma_f32_16x16x32_bf16 v[112:115], v[160:163], v[196:199], v[112:115]
	v_mfma_f32_16x16x32_bf16 v[108:111], v[180:183], v[196:199], v[108:111]
	v_mfma_f32_16x16x32_bf16 v[96:99], v[160:163], v[204:207], v[96:99]
	v_mfma_f32_16x16x32_bf16 v[92:95], v[180:183], v[204:207], v[92:95]
	v_mfma_f32_16x16x32_bf16 v[76:79], v[160:163], v[224:227], v[76:79]
	v_mfma_f32_16x16x32_bf16 v[72:75], v[180:183], v[224:227], v[72:75]
	v_mfma_f32_16x16x32_bf16 v[124:127], v[176:179], v[192:195], v[124:127]
	v_mfma_f32_16x16x32_bf16 v[128:131], v[184:187], v[192:195], v[128:131]
	v_mfma_f32_16x16x32_bf16 v[112:115], v[176:179], v[200:203], v[112:115]
	v_mfma_f32_16x16x32_bf16 v[108:111], v[184:187], v[200:203], v[108:111]
	v_mfma_f32_16x16x32_bf16 v[96:99], v[176:179], v[218:221], v[96:99]
	v_mfma_f32_16x16x32_bf16 v[92:95], v[184:187], v[218:221], v[92:95]
	v_mfma_f32_16x16x32_bf16 v[76:79], v[176:179], v[228:231], v[76:79]
	v_mfma_f32_16x16x32_bf16 v[72:75], v[184:187], v[228:231], v[72:75]
	s_setprio 0
	s_barrier
	s_add_i32 s20, 0, 0x1c000
	s_add_i32 s21, s22, s28
	v_add_u32_e32 v169, s20, v158
	v_lshl_add_u64 v[164:165], v[164:165], 0, s[88:89]
	s_mov_b32 m0, s21
	ds_read_b128 v[232:235], v169
	ds_read_b128 v[236:239], v169 offset:1024
	ds_read_b128 v[240:243], v169 offset:2048
	ds_read_b128 v[244:247], v169 offset:3072
	global_load_lds_dwordx4 v[164:165], off
	v_lshl_add_u64 v[164:165], v[248:249], 0, s[88:89]
	s_add_i32 m0, s21, 0x2000
	s_nop 0
	global_load_lds_dwordx4 v[164:165], off
	v_cvt_pk_bf16_f32 v124, v124, v125
	v_cvt_pk_bf16_f32 v125, v126, v127
	v_cvt_pk_bf16_f32 v126, v128, v129
	v_cvt_pk_bf16_f32 v127, v130, v131
	s_add_u32 s78, s98, 0x0
	s_addc_u32 s79, s99, 0
	global_store_dwordx4 v138, v[124:127], s[78:79] nt
	s_waitcnt vmcnt(11)
	s_barrier
	s_waitcnt lgkmcnt(0)
	s_setprio 1
	s_waitcnt lgkmcnt(0)
	v_mfma_f32_16x16x32_bf16 v[120:123], v[232:235], v[188:191], v[120:123]
	v_mfma_f32_16x16x32_bf16 v[116:119], v[240:243], v[188:191], v[116:119]
	v_mfma_f32_16x16x32_bf16 v[104:107], v[232:235], v[196:199], v[104:107]
	v_mfma_f32_16x16x32_bf16 v[100:103], v[240:243], v[196:199], v[100:103]
	v_mfma_f32_16x16x32_bf16 v[88:91], v[232:235], v[204:207], v[88:91]
	v_mfma_f32_16x16x32_bf16 v[84:87], v[240:243], v[204:207], v[84:87]
	v_mfma_f32_16x16x32_bf16 v[68:71], v[232:235], v[224:227], v[68:71]
	v_mfma_f32_16x16x32_bf16 v[64:67], v[240:243], v[224:227], v[64:67]
	v_mfma_f32_16x16x32_bf16 v[120:123], v[236:239], v[192:195], v[120:123]
	v_mfma_f32_16x16x32_bf16 v[116:119], v[244:247], v[192:195], v[116:119]
	v_mfma_f32_16x16x32_bf16 v[104:107], v[236:239], v[200:203], v[104:107]
	v_mfma_f32_16x16x32_bf16 v[100:103], v[244:247], v[200:203], v[100:103]
	v_mfma_f32_16x16x32_bf16 v[88:91], v[236:239], v[218:221], v[88:91]
	v_mfma_f32_16x16x32_bf16 v[84:87], v[244:247], v[218:221], v[84:87]
	v_mfma_f32_16x16x32_bf16 v[68:71], v[236:239], v[228:231], v[68:71]
	v_mfma_f32_16x16x32_bf16 v[64:67], v[244:247], v[228:231], v[64:67]
	s_setprio 0
	s_mov_b32 m0, s36
	v_lshl_add_u64 v[164:165], v[250:251], 0, s[88:89]
	s_barrier
	ds_read_b128 v[188:191], v159 offset:49152
	ds_read_b128 v[192:195], v159 offset:50176
	ds_read_b128 v[196:199], v159 offset:51200
	ds_read_b128 v[200:203], v159 offset:52224
	ds_read_b128 v[204:207], v159 offset:53248
	ds_read_b128 v[218:221], v159 offset:54272
	ds_read_b128 v[224:227], v159 offset:55296
	ds_read_b128 v[228:231], v159 offset:56320
	global_load_lds_dwordx4 v[164:165], off
	v_lshl_add_u64 v[164:165], v[210:211], 0, s[88:89]
	s_mov_b32 m0, s37
	s_nop 0
	global_load_lds_dwordx4 v[164:165], off
	v_cvt_pk_bf16_f32 v112, v112, v113
	v_cvt_pk_bf16_f32 v113, v114, v115
	v_cvt_pk_bf16_f32 v114, v108, v109
	v_cvt_pk_bf16_f32 v115, v110, v111
	s_add_u32 s78, s98, 0x2000
	s_addc_u32 s79, s99, 0
	global_store_dwordx4 v138, v[112:115], s[78:79] nt
	s_barrier
	s_waitcnt lgkmcnt(0)
	s_setprio 1
	s_waitcnt lgkmcnt(0)
	v_mfma_f32_16x16x32_bf16 v[60:63], v[160:163], v[188:191], v[60:63]
	v_mfma_f32_16x16x32_bf16 v[56:59], v[180:183], v[188:191], v[56:59]
	v_mfma_f32_16x16x32_bf16 v[44:47], v[160:163], v[196:199], v[44:47]
	v_mfma_f32_16x16x32_bf16 v[40:43], v[180:183], v[196:199], v[40:43]
	v_mfma_f32_16x16x32_bf16 v[28:31], v[160:163], v[204:207], v[28:31]
	v_mfma_f32_16x16x32_bf16 v[24:27], v[180:183], v[204:207], v[24:27]
	v_mfma_f32_16x16x32_bf16 v[12:15], v[160:163], v[224:227], v[12:15]
	v_mfma_f32_16x16x32_bf16 v[8:11], v[180:183], v[224:227], v[8:11]
	v_mfma_f32_16x16x32_bf16 v[60:63], v[176:179], v[192:195], v[60:63]
	v_mfma_f32_16x16x32_bf16 v[56:59], v[184:187], v[192:195], v[56:59]
	v_mfma_f32_16x16x32_bf16 v[44:47], v[176:179], v[200:203], v[44:47]
	v_mfma_f32_16x16x32_bf16 v[40:43], v[184:187], v[200:203], v[40:43]
	v_mfma_f32_16x16x32_bf16 v[28:31], v[176:179], v[218:221], v[28:31]
	v_mfma_f32_16x16x32_bf16 v[24:27], v[184:187], v[218:221], v[24:27]
	v_mfma_f32_16x16x32_bf16 v[12:15], v[176:179], v[228:231], v[12:15]
	v_mfma_f32_16x16x32_bf16 v[8:11], v[184:187], v[228:231], v[8:11]
	s_setprio 0
	s_barrier
	s_add_i32 s20, s20, s28
	v_lshl_add_u64 v[160:161], v[170:171], 0, s[88:89]
	s_mov_b32 m0, s20
	s_nop 0
	global_load_lds_dwordx4 v[160:161], off
	v_lshl_add_u64 v[160:161], v[172:173], 0, s[88:89]
	s_add_i32 m0, s20, 0x2000
	s_nop 0
	global_load_lds_dwordx4 v[160:161], off
	v_cvt_pk_bf16_f32 v96, v96, v97
	v_cvt_pk_bf16_f32 v97, v98, v99
	v_cvt_pk_bf16_f32 v98, v92, v93
	v_cvt_pk_bf16_f32 v99, v94, v95
	s_add_u32 s78, s98, 0x4000
	s_addc_u32 s79, s99, 0
	global_store_dwordx4 v138, v[96:99], s[78:79] nt
	s_waitcnt vmcnt(9)
	s_barrier
	s_setprio 1
	v_mfma_f32_16x16x32_bf16 v[52:55], v[232:235], v[188:191], v[52:55]
	v_mfma_f32_16x16x32_bf16 v[48:51], v[240:243], v[188:191], v[48:51]
	v_mfma_f32_16x16x32_bf16 v[36:39], v[232:235], v[196:199], v[36:39]
	v_mfma_f32_16x16x32_bf16 v[32:35], v[240:243], v[196:199], v[32:35]
	v_mfma_f32_16x16x32_bf16 v[20:23], v[232:235], v[204:207], v[20:23]
	v_mfma_f32_16x16x32_bf16 v[16:19], v[240:243], v[204:207], v[16:19]
	v_mfma_f32_16x16x32_bf16 v[4:7], v[232:235], v[224:227], v[4:7]
	v_mfma_f32_16x16x32_bf16 v[0:3], v[240:243], v[224:227], v[0:3]
	v_mfma_f32_16x16x32_bf16 v[52:55], v[236:239], v[192:195], v[52:55]
	v_mfma_f32_16x16x32_bf16 v[48:51], v[244:247], v[192:195], v[48:51]
	v_mfma_f32_16x16x32_bf16 v[36:39], v[236:239], v[200:203], v[36:39]
	v_mfma_f32_16x16x32_bf16 v[32:35], v[244:247], v[200:203], v[32:35]
	v_mfma_f32_16x16x32_bf16 v[20:23], v[236:239], v[218:221], v[20:23]
	v_mfma_f32_16x16x32_bf16 v[16:19], v[244:247], v[218:221], v[16:19]
	v_mfma_f32_16x16x32_bf16 v[4:7], v[236:239], v[228:231], v[4:7]
	v_mfma_f32_16x16x32_bf16 v[0:3], v[244:247], v[228:231], v[0:3]
	s_setprio 0
	s_add_u32 s44, s44, 0x100
	s_addc_u32 s45, s45, 0
	s_add_u32 s18, s18, 0x100
	s_addc_u32 s19, s19, 0
	s_mov_b32 s20, s46
	s_barrier
	s_and_b64 vcc, exec, s[6:7]
	s_cbranch_vccz .Lp2_next
	s_mov_b32 s47, 0x28000
	v_mov_b64_e32 v[246:247], v[174:175]
	v_mov_b64_e32 v[174:175], v[216:217]
	v_mov_b32_e32 v217, v209
	v_mov_b32_e32 v209, 0x7f800000
	s_branch .LBB0_214

.LBB0_1755:
	s_add_i32 s50, s24, 2
	s_add_u32 s26, s8, 0x80
	s_addc_u32 s25, s9, 0
	s_add_i32 s51, 0, 0x10000
	v_add_u32_e32 v144, s51, v218
	ds_read_b128 v[132:135], v144
	ds_read_b128 v[136:139], v144 offset:1024
	ds_read_b128 v[140:143], v144 offset:2048
	ds_read_b128 v[144:147], v144 offset:3072
	s_cmp_eq_u32 s42, s24
	s_cselect_b32 s24, s20, s26
	s_cselect_b32 s25, s21, s25
	s_cselect_b32 s27, s23, s49
	s_cselect_b32 s26, s22, s19
	v_lshl_add_u64 v[164:165], s[8:9], 0, v[192:193]
	s_add_i32 m0, s35, 0xc000
	ds_read_b128 v[148:151], v220
	ds_read_b128 v[152:155], v220 offset:1024
	ds_read_b128 v[156:159], v220 offset:2048
	ds_read_b128 v[160:163], v220 offset:3072
	ds_read_b128 v[194:197], v220 offset:4096
	ds_read_b128 v[198:201], v220 offset:5120
	ds_read_b128 v[202:205], v220 offset:6144
	ds_read_b128 v[224:227], v220 offset:7168
	global_load_lds_dwordx4 v[164:165], off
	v_lshl_add_u64 v[164:165], s[8:9], 0, v[190:191]
	s_add_i32 m0, s35, 0xe000
	s_nop 0
	global_load_lds_dwordx4 v[164:165], off
	s_waitcnt lgkmcnt(8)
	s_waitcnt vmcnt(10)
	s_barrier
	s_waitcnt lgkmcnt(0)
	s_setprio 1
	s_waitcnt lgkmcnt(0)
	v_mfma_f32_16x16x32_bf16 v[128:131], v[132:135], v[148:151], v[128:131]
	v_mfma_f32_16x16x32_bf16 v[124:127], v[140:143], v[148:151], v[124:127]
	v_mfma_f32_16x16x32_bf16 v[112:115], v[132:135], v[156:159], v[112:115]
	v_mfma_f32_16x16x32_bf16 v[108:111], v[140:143], v[156:159], v[108:111]
	v_mfma_f32_16x16x32_bf16 v[96:99], v[132:135], v[194:197], v[96:99]
	v_mfma_f32_16x16x32_bf16 v[92:95], v[140:143], v[194:197], v[92:95]
	v_mfma_f32_16x16x32_bf16 v[76:79], v[132:135], v[202:205], v[76:79]
	v_mfma_f32_16x16x32_bf16 v[72:75], v[140:143], v[202:205], v[72:75]
	v_mfma_f32_16x16x32_bf16 v[128:131], v[136:139], v[152:155], v[128:131]
	v_mfma_f32_16x16x32_bf16 v[124:127], v[144:147], v[152:155], v[124:127]
	v_mfma_f32_16x16x32_bf16 v[112:115], v[136:139], v[160:163], v[112:115]
	v_mfma_f32_16x16x32_bf16 v[108:111], v[144:147], v[160:163], v[108:111]
	v_mfma_f32_16x16x32_bf16 v[96:99], v[136:139], v[198:201], v[96:99]
	v_mfma_f32_16x16x32_bf16 v[92:95], v[144:147], v[198:201], v[92:95]
	v_mfma_f32_16x16x32_bf16 v[76:79], v[136:139], v[224:227], v[76:79]
	v_mfma_f32_16x16x32_bf16 v[72:75], v[144:147], v[224:227], v[72:75]
	s_setprio 0
	s_barrier
	s_add_i32 s52, 0, 0x14000
	v_add_u32_e32 v164, s52, v218
	s_add_i32 s51, s51, s34
	ds_read_b128 v[228:231], v164
	ds_read_b128 v[232:235], v164 offset:1024
	ds_read_b128 v[236:239], v164 offset:2048
	ds_read_b128 v[240:243], v164 offset:3072
	v_lshl_add_u64 v[164:165], s[26:27], 0, v[182:183]
	s_mov_b32 m0, s51
	v_lshl_add_u64 v[170:171], s[26:27], 0, v[178:179]
	global_load_lds_dwordx4 v[164:165], off
	s_add_i32 m0, s51, 0x2000
	s_nop 0
	global_load_lds_dwordx4 v[170:171], off
	s_waitcnt vmcnt(10)
	s_barrier
	s_waitcnt lgkmcnt(0)
	s_setprio 1
	s_waitcnt lgkmcnt(0)
	v_mfma_f32_16x16x32_bf16 v[120:123], v[228:231], v[148:151], v[120:123]
	v_mfma_f32_16x16x32_bf16 v[116:119], v[236:239], v[148:151], v[116:119]
	v_mfma_f32_16x16x32_bf16 v[104:107], v[228:231], v[156:159], v[104:107]
	v_mfma_f32_16x16x32_bf16 v[100:103], v[236:239], v[156:159], v[100:103]
	v_mfma_f32_16x16x32_bf16 v[88:91], v[228:231], v[194:197], v[88:91]
	v_mfma_f32_16x16x32_bf16 v[84:87], v[236:239], v[194:197], v[84:87]
	v_mfma_f32_16x16x32_bf16 v[68:71], v[228:231], v[202:205], v[68:71]
	v_mfma_f32_16x16x32_bf16 v[64:67], v[236:239], v[202:205], v[64:67]
	v_mfma_f32_16x16x32_bf16 v[120:123], v[232:235], v[152:155], v[120:123]
	v_mfma_f32_16x16x32_bf16 v[116:119], v[240:243], v[152:155], v[116:119]
	v_mfma_f32_16x16x32_bf16 v[104:107], v[232:235], v[160:163], v[104:107]
	v_mfma_f32_16x16x32_bf16 v[100:103], v[240:243], v[160:163], v[100:103]
	v_mfma_f32_16x16x32_bf16 v[88:91], v[232:235], v[198:201], v[88:91]
	v_mfma_f32_16x16x32_bf16 v[84:87], v[240:243], v[198:201], v[84:87]
	v_mfma_f32_16x16x32_bf16 v[68:71], v[232:235], v[224:227], v[68:71]
	v_mfma_f32_16x16x32_bf16 v[64:67], v[240:243], v[224:227], v[64:67]
	s_setprio 0
	s_mov_b32 m0, s35
	v_lshl_add_u64 v[172:173], s[24:25], 0, v[184:185]
	s_barrier
	ds_read_b128 v[148:151], v220 offset:16384
	ds_read_b128 v[152:155], v220 offset:17408
	ds_read_b128 v[156:159], v220 offset:18432
	ds_read_b128 v[160:163], v220 offset:19456
	ds_read_b128 v[194:197], v220 offset:20480
	ds_read_b128 v[198:201], v220 offset:21504
	ds_read_b128 v[202:205], v220 offset:22528
	ds_read_b128 v[224:227], v220 offset:23552
	global_load_lds_dwordx4 v[172:173], off
	v_lshl_add_u64 v[206:207], s[24:25], 0, v[180:181]
	s_mov_b32 m0, s36
	s_nop 0
	global_load_lds_dwordx4 v[206:207], off
	s_barrier
	s_waitcnt lgkmcnt(0)
	s_setprio 1
	s_waitcnt lgkmcnt(0)
	v_mfma_f32_16x16x32_bf16 v[60:63], v[132:135], v[148:151], v[60:63]
	v_mfma_f32_16x16x32_bf16 v[56:59], v[140:143], v[148:151], v[56:59]
	v_mfma_f32_16x16x32_bf16 v[44:47], v[132:135], v[156:159], v[44:47]
	v_mfma_f32_16x16x32_bf16 v[40:43], v[140:143], v[156:159], v[40:43]
	v_mfma_f32_16x16x32_bf16 v[28:31], v[132:135], v[194:197], v[28:31]
	v_mfma_f32_16x16x32_bf16 v[24:27], v[140:143], v[194:197], v[24:27]
	v_mfma_f32_16x16x32_bf16 v[12:15], v[132:135], v[202:205], v[12:15]
	v_mfma_f32_16x16x32_bf16 v[8:11], v[140:143], v[202:205], v[8:11]
	v_mfma_f32_16x16x32_bf16 v[60:63], v[136:139], v[152:155], v[60:63]
	v_mfma_f32_16x16x32_bf16 v[56:59], v[144:147], v[152:155], v[56:59]
	v_mfma_f32_16x16x32_bf16 v[44:47], v[136:139], v[160:163], v[44:47]
	v_mfma_f32_16x16x32_bf16 v[40:43], v[144:147], v[160:163], v[40:43]
	v_mfma_f32_16x16x32_bf16 v[28:31], v[136:139], v[198:201], v[28:31]
	v_mfma_f32_16x16x32_bf16 v[24:27], v[144:147], v[198:201], v[24:27]
	v_mfma_f32_16x16x32_bf16 v[12:15], v[136:139], v[224:227], v[12:15]
	v_mfma_f32_16x16x32_bf16 v[8:11], v[144:147], v[224:227], v[8:11]
	s_setprio 0
	s_barrier
	s_add_u32 s26, s26, s10
	s_addc_u32 s27, s27, s11
	s_add_i32 s51, s52, s34
	v_lshl_add_u64 v[210:211], s[26:27], 0, v[182:183]
	s_mov_b32 m0, s51
	v_lshl_add_u64 v[244:245], s[26:27], 0, v[178:179]
	global_load_lds_dwordx4 v[210:211], off
	s_add_i32 m0, s51, 0x2000
	s_nop 0
	global_load_lds_dwordx4 v[244:245], off
	s_waitcnt vmcnt(10)
	s_barrier
	s_setprio 1
	v_mfma_f32_16x16x32_bf16 v[52:55], v[228:231], v[148:151], v[52:55]
	v_mfma_f32_16x16x32_bf16 v[48:51], v[236:239], v[148:151], v[48:51]
	v_mfma_f32_16x16x32_bf16 v[36:39], v[228:231], v[156:159], v[36:39]
	v_mfma_f32_16x16x32_bf16 v[32:35], v[236:239], v[156:159], v[32:35]
	v_mfma_f32_16x16x32_bf16 v[20:23], v[228:231], v[194:197], v[20:23]
	v_mfma_f32_16x16x32_bf16 v[16:19], v[236:239], v[194:197], v[16:19]
	v_mfma_f32_16x16x32_bf16 v[4:7], v[228:231], v[202:205], v[4:7]
	v_mfma_f32_16x16x32_bf16 v[0:3], v[236:239], v[202:205], v[0:3]
	v_mfma_f32_16x16x32_bf16 v[52:55], v[232:235], v[152:155], v[52:55]
	v_mfma_f32_16x16x32_bf16 v[48:51], v[240:243], v[152:155], v[48:51]
	v_mfma_f32_16x16x32_bf16 v[36:39], v[232:235], v[160:163], v[36:39]
	v_mfma_f32_16x16x32_bf16 v[32:35], v[240:243], v[160:163], v[32:35]
	v_mfma_f32_16x16x32_bf16 v[20:23], v[232:235], v[198:201], v[20:23]
	v_mfma_f32_16x16x32_bf16 v[16:19], v[240:243], v[198:201], v[16:19]
	v_mfma_f32_16x16x32_bf16 v[4:7], v[232:235], v[224:227], v[4:7]
	v_mfma_f32_16x16x32_bf16 v[0:3], v[240:243], v[224:227], v[0:3]
	s_setprio 0
	s_add_i32 s26, 0, 0x18000
	v_add_u32_e32 v144, s26, v218
	s_barrier
	ds_read_b128 v[132:135], v144
	ds_read_b128 v[136:139], v144 offset:1024
	ds_read_b128 v[140:143], v144 offset:2048
	ds_read_b128 v[144:147], v144 offset:3072
	s_add_u32 s24, s24, s10
	s_addc_u32 s25, s25, s11
	s_mov_b32 m0, s37
	v_lshl_add_u64 v[228:229], s[24:25], 0, v[184:185]
	ds_read_b128 v[148:151], v220 offset:32768
	ds_read_b128 v[152:155], v220 offset:33792
	ds_read_b128 v[156:159], v220 offset:34816
	ds_read_b128 v[160:163], v220 offset:35840
	ds_read_b128 v[194:197], v220 offset:36864
	ds_read_b128 v[198:201], v220 offset:37888
	ds_read_b128 v[202:205], v220 offset:38912
	ds_read_b128 v[224:227], v220 offset:39936
	global_load_lds_dwordx4 v[228:229], off
	v_lshl_add_u64 v[228:229], s[24:25], 0, v[180:181]
	s_mov_b32 m0, s38
	s_nop 0
	global_load_lds_dwordx4 v[228:229], off
	s_waitcnt lgkmcnt(8)
	s_waitcnt vmcnt(10)
	s_barrier
	s_waitcnt lgkmcnt(0)
	s_setprio 1
	s_waitcnt lgkmcnt(0)
	v_mfma_f32_16x16x32_bf16 v[128:131], v[132:135], v[148:151], v[128:131]
	v_mfma_f32_16x16x32_bf16 v[124:127], v[140:143], v[148:151], v[124:127]
	v_mfma_f32_16x16x32_bf16 v[112:115], v[132:135], v[156:159], v[112:115]
	v_mfma_f32_16x16x32_bf16 v[108:111], v[140:143], v[156:159], v[108:111]
	v_mfma_f32_16x16x32_bf16 v[96:99], v[132:135], v[194:197], v[96:99]
	v_mfma_f32_16x16x32_bf16 v[92:95], v[140:143], v[194:197], v[92:95]
	v_mfma_f32_16x16x32_bf16 v[76:79], v[132:135], v[202:205], v[76:79]
	v_mfma_f32_16x16x32_bf16 v[72:75], v[140:143], v[202:205], v[72:75]
	v_mfma_f32_16x16x32_bf16 v[128:131], v[136:139], v[152:155], v[128:131]
	v_mfma_f32_16x16x32_bf16 v[124:127], v[144:147], v[152:155], v[124:127]
	v_mfma_f32_16x16x32_bf16 v[112:115], v[136:139], v[160:163], v[112:115]
	v_mfma_f32_16x16x32_bf16 v[108:111], v[144:147], v[160:163], v[108:111]
	v_mfma_f32_16x16x32_bf16 v[96:99], v[136:139], v[198:201], v[96:99]
	v_mfma_f32_16x16x32_bf16 v[92:95], v[144:147], v[198:201], v[92:95]
	v_mfma_f32_16x16x32_bf16 v[76:79], v[136:139], v[224:227], v[76:79]
	v_mfma_f32_16x16x32_bf16 v[72:75], v[144:147], v[224:227], v[72:75]
	s_setprio 0
	s_barrier
	s_add_i32 s24, 0, 0x1c000
	s_add_i32 s25, s26, s34
	v_add_u32_e32 v166, s24, v218
	v_lshl_add_u64 v[164:165], v[164:165], 0, s[88:89]
	s_mov_b32 m0, s25
	ds_read_b128 v[228:231], v166
	ds_read_b128 v[232:235], v166 offset:1024
	ds_read_b128 v[236:239], v166 offset:2048
	ds_read_b128 v[240:243], v166 offset:3072
	global_load_lds_dwordx4 v[164:165], off
	v_lshl_add_u64 v[164:165], v[170:171], 0, s[88:89]
	s_add_i32 m0, s25, 0x2000
	s_nop 0
	global_load_lds_dwordx4 v[164:165], off
	s_waitcnt vmcnt(10)
	s_barrier
	s_waitcnt lgkmcnt(0)
	s_setprio 1
	s_waitcnt lgkmcnt(0)
	v_mfma_f32_16x16x32_bf16 v[120:123], v[228:231], v[148:151], v[120:123]
	v_mfma_f32_16x16x32_bf16 v[116:119], v[236:239], v[148:151], v[116:119]
	v_mfma_f32_16x16x32_bf16 v[104:107], v[228:231], v[156:159], v[104:107]
	v_mfma_f32_16x16x32_bf16 v[100:103], v[236:239], v[156:159], v[100:103]
	v_mfma_f32_16x16x32_bf16 v[88:91], v[228:231], v[194:197], v[88:91]
	v_mfma_f32_16x16x32_bf16 v[84:87], v[236:239], v[194:197], v[84:87]
	v_mfma_f32_16x16x32_bf16 v[68:71], v[228:231], v[202:205], v[68:71]
	v_mfma_f32_16x16x32_bf16 v[64:67], v[236:239], v[202:205], v[64:67]
	v_mfma_f32_16x16x32_bf16 v[120:123], v[232:235], v[152:155], v[120:123]
	v_mfma_f32_16x16x32_bf16 v[116:119], v[240:243], v[152:155], v[116:119]
	v_mfma_f32_16x16x32_bf16 v[104:107], v[232:235], v[160:163], v[104:107]
	v_mfma_f32_16x16x32_bf16 v[100:103], v[240:243], v[160:163], v[100:103]
	v_mfma_f32_16x16x32_bf16 v[88:91], v[232:235], v[198:201], v[88:91]
	v_mfma_f32_16x16x32_bf16 v[84:87], v[240:243], v[198:201], v[84:87]
	v_mfma_f32_16x16x32_bf16 v[68:71], v[232:235], v[224:227], v[68:71]
	v_mfma_f32_16x16x32_bf16 v[64:67], v[240:243], v[224:227], v[64:67]
	s_setprio 0
	s_mov_b32 m0, s39
	v_lshl_add_u64 v[164:165], v[172:173], 0, s[88:89]
	s_barrier
	ds_read_b128 v[148:151], v220 offset:49152
	ds_read_b128 v[152:155], v220 offset:50176
	ds_read_b128 v[156:159], v220 offset:51200
	ds_read_b128 v[160:163], v220 offset:52224
	ds_read_b128 v[194:197], v220 offset:53248
	ds_read_b128 v[198:201], v220 offset:54272
	ds_read_b128 v[202:205], v220 offset:55296
	ds_read_b128 v[224:227], v220 offset:56320
	global_load_lds_dwordx4 v[164:165], off
	v_lshl_add_u64 v[164:165], v[206:207], 0, s[88:89]
	s_mov_b32 m0, s40
	s_nop 0
	global_load_lds_dwordx4 v[164:165], off
	s_barrier
	s_waitcnt lgkmcnt(0)
	s_setprio 1
	s_waitcnt lgkmcnt(0)
	v_mfma_f32_16x16x32_bf16 v[60:63], v[132:135], v[148:151], v[60:63]
	v_mfma_f32_16x16x32_bf16 v[56:59], v[140:143], v[148:151], v[56:59]
	v_mfma_f32_16x16x32_bf16 v[44:47], v[132:135], v[156:159], v[44:47]
	v_mfma_f32_16x16x32_bf16 v[40:43], v[140:143], v[156:159], v[40:43]
	v_mfma_f32_16x16x32_bf16 v[28:31], v[132:135], v[194:197], v[28:31]
	v_mfma_f32_16x16x32_bf16 v[24:27], v[140:143], v[194:197], v[24:27]
	v_mfma_f32_16x16x32_bf16 v[12:15], v[132:135], v[202:205], v[12:15]
	v_mfma_f32_16x16x32_bf16 v[8:11], v[140:143], v[202:205], v[8:11]
	v_mfma_f32_16x16x32_bf16 v[60:63], v[136:139], v[152:155], v[60:63]
	v_mfma_f32_16x16x32_bf16 v[56:59], v[144:147], v[152:155], v[56:59]
	v_mfma_f32_16x16x32_bf16 v[44:47], v[136:139], v[160:163], v[44:47]
	v_mfma_f32_16x16x32_bf16 v[40:43], v[144:147], v[160:163], v[40:43]
	v_mfma_f32_16x16x32_bf16 v[28:31], v[136:139], v[198:201], v[28:31]
	v_mfma_f32_16x16x32_bf16 v[24:27], v[144:147], v[198:201], v[24:27]
	v_mfma_f32_16x16x32_bf16 v[12:15], v[136:139], v[224:227], v[12:15]
	v_mfma_f32_16x16x32_bf16 v[8:11], v[144:147], v[224:227], v[8:11]
	s_setprio 0
	s_barrier
	s_add_i32 s24, s24, s34
	v_lshl_add_u64 v[132:133], v[210:211], 0, s[88:89]
	s_mov_b32 m0, s24
	s_nop 0
	global_load_lds_dwordx4 v[132:133], off
	v_lshl_add_u64 v[132:133], v[244:245], 0, s[88:89]
	s_add_i32 m0, s24, 0x2000
	s_nop 0
	global_load_lds_dwordx4 v[132:133], off
	s_waitcnt vmcnt(10)
	s_barrier
	s_setprio 1
	v_mfma_f32_16x16x32_bf16 v[52:55], v[228:231], v[148:151], v[52:55]
	v_mfma_f32_16x16x32_bf16 v[48:51], v[236:239], v[148:151], v[48:51]
	v_mfma_f32_16x16x32_bf16 v[36:39], v[228:231], v[156:159], v[36:39]
	v_mfma_f32_16x16x32_bf16 v[32:35], v[236:239], v[156:159], v[32:35]
	v_mfma_f32_16x16x32_bf16 v[20:23], v[228:231], v[194:197], v[20:23]
	v_mfma_f32_16x16x32_bf16 v[16:19], v[236:239], v[194:197], v[16:19]
	v_mfma_f32_16x16x32_bf16 v[4:7], v[228:231], v[202:205], v[4:7]
	v_mfma_f32_16x16x32_bf16 v[0:3], v[236:239], v[202:205], v[0:3]
	v_mfma_f32_16x16x32_bf16 v[52:55], v[232:235], v[152:155], v[52:55]
	v_mfma_f32_16x16x32_bf16 v[48:51], v[240:243], v[152:155], v[48:51]
	v_mfma_f32_16x16x32_bf16 v[36:39], v[232:235], v[160:163], v[36:39]
	v_mfma_f32_16x16x32_bf16 v[32:35], v[240:243], v[160:163], v[32:35]
	v_mfma_f32_16x16x32_bf16 v[20:23], v[232:235], v[198:201], v[20:23]
	v_mfma_f32_16x16x32_bf16 v[16:19], v[240:243], v[198:201], v[16:19]
	v_mfma_f32_16x16x32_bf16 v[4:7], v[232:235], v[224:227], v[4:7]
	v_mfma_f32_16x16x32_bf16 v[0:3], v[240:243], v[224:227], v[0:3]
	s_setprio 0
	s_add_u32 s19, s19, 0x100
	s_addc_u32 s49, s49, 0
	s_add_u32 s8, s8, 0x100
	s_addc_u32 s9, s9, 0
	s_cmp_ge_i32 s50, s41
	s_mov_b32 s24, s50
	s_barrier
	s_cbranch_scc0 .LBB0_1755
	s_movk_i32 s52, 0x880
	s_movk_i32 s50, 0x110
	v_readlane_b32 s51, v254, 48

.LBB0_1810:
	s_add_i32 s46, s20, 2
	s_add_u32 s22, s18, 0x80
	s_addc_u32 s21, s19, 0
	s_add_i32 s47, 0, 0x10000
	v_add_u32_e32 v144, s47, v196
	ds_read_b128 v[132:135], v144
	ds_read_b128 v[136:139], v144 offset:1024
	ds_read_b128 v[140:143], v144 offset:2048
	ds_read_b128 v[144:147], v144 offset:3072
	s_cmp_eq_u32 s38, s20
	s_cselect_b32 s20, s10, s22
	s_cselect_b32 s21, s11, s21
	s_cselect_b32 s23, s13, s45
	s_cselect_b32 s22, s12, s44
	v_lshl_add_u64 v[170:171], s[18:19], 0, v[182:183]
	s_add_i32 m0, s29, 0xc000
	ds_read_b128 v[148:151], v198
	ds_read_b128 v[152:155], v198 offset:1024
	ds_read_b128 v[184:187], v198 offset:2048
	ds_read_b128 v[188:191], v198 offset:3072
	ds_read_b128 v[192:195], v198 offset:4096
	ds_read_b128 v[200:203], v198 offset:5120
	ds_read_b128 v[204:207], v198 offset:6144
	ds_read_b128 v[218:221], v198 offset:7168
	global_load_lds_dwordx4 v[170:171], off
	v_lshl_add_u64 v[170:171], s[18:19], 0, v[180:181]
	s_add_i32 m0, s29, 0xe000
	s_nop 0
	global_load_lds_dwordx4 v[170:171], off
	s_waitcnt lgkmcnt(8)
	s_waitcnt vmcnt(10)
	s_barrier
	s_waitcnt lgkmcnt(0)
	s_setprio 1
	s_waitcnt lgkmcnt(0)
	v_mfma_f32_16x16x32_bf16 v[128:131], v[132:135], v[148:151], v[128:131]
	v_mfma_f32_16x16x32_bf16 v[124:127], v[140:143], v[148:151], v[124:127]
	v_mfma_f32_16x16x32_bf16 v[112:115], v[132:135], v[184:187], v[112:115]
	v_mfma_f32_16x16x32_bf16 v[108:111], v[140:143], v[184:187], v[108:111]
	v_mfma_f32_16x16x32_bf16 v[96:99], v[132:135], v[192:195], v[96:99]
	v_mfma_f32_16x16x32_bf16 v[92:95], v[140:143], v[192:195], v[92:95]
	v_mfma_f32_16x16x32_bf16 v[76:79], v[132:135], v[204:207], v[76:79]
	v_mfma_f32_16x16x32_bf16 v[72:75], v[140:143], v[204:207], v[72:75]
	v_mfma_f32_16x16x32_bf16 v[128:131], v[136:139], v[152:155], v[128:131]
	v_mfma_f32_16x16x32_bf16 v[124:127], v[144:147], v[152:155], v[124:127]
	v_mfma_f32_16x16x32_bf16 v[112:115], v[136:139], v[188:191], v[112:115]
	v_mfma_f32_16x16x32_bf16 v[108:111], v[144:147], v[188:191], v[108:111]
	v_mfma_f32_16x16x32_bf16 v[96:99], v[136:139], v[200:203], v[96:99]
	v_mfma_f32_16x16x32_bf16 v[92:95], v[144:147], v[200:203], v[92:95]
	v_mfma_f32_16x16x32_bf16 v[76:79], v[136:139], v[218:221], v[76:79]
	v_mfma_f32_16x16x32_bf16 v[72:75], v[144:147], v[218:221], v[72:75]
	s_setprio 0
	s_barrier
	s_add_i32 s48, 0, 0x14000
	s_add_i32 s47, s47, s28
	v_add_u32_e32 v166, s48, v196
	v_lshl_add_u64 v[170:171], s[22:23], 0, v[160:161]
	s_mov_b32 m0, s47
	ds_read_b128 v[224:227], v166
	ds_read_b128 v[228:231], v166 offset:1024
	ds_read_b128 v[232:235], v166 offset:2048
	ds_read_b128 v[236:239], v166 offset:3072
	global_load_lds_dwordx4 v[170:171], off
	v_lshl_add_u64 v[172:173], s[22:23], 0, v[156:157]
	s_add_i32 m0, s47, 0x2000
	s_nop 0
	global_load_lds_dwordx4 v[172:173], off
	s_waitcnt vmcnt(10)
	s_barrier
	s_waitcnt lgkmcnt(0)
	s_setprio 1
	s_waitcnt lgkmcnt(0)
	v_mfma_f32_16x16x32_bf16 v[120:123], v[224:227], v[148:151], v[120:123]
	v_mfma_f32_16x16x32_bf16 v[116:119], v[232:235], v[148:151], v[116:119]
	v_mfma_f32_16x16x32_bf16 v[104:107], v[224:227], v[184:187], v[104:107]
	v_mfma_f32_16x16x32_bf16 v[100:103], v[232:235], v[184:187], v[100:103]
	v_mfma_f32_16x16x32_bf16 v[88:91], v[224:227], v[192:195], v[88:91]
	v_mfma_f32_16x16x32_bf16 v[84:87], v[232:235], v[192:195], v[84:87]
	v_mfma_f32_16x16x32_bf16 v[68:71], v[224:227], v[204:207], v[68:71]
	v_mfma_f32_16x16x32_bf16 v[64:67], v[232:235], v[204:207], v[64:67]
	v_mfma_f32_16x16x32_bf16 v[120:123], v[228:231], v[152:155], v[120:123]
	v_mfma_f32_16x16x32_bf16 v[116:119], v[236:239], v[152:155], v[116:119]
	v_mfma_f32_16x16x32_bf16 v[104:107], v[228:231], v[188:191], v[104:107]
	v_mfma_f32_16x16x32_bf16 v[100:103], v[236:239], v[188:191], v[100:103]
	v_mfma_f32_16x16x32_bf16 v[88:91], v[228:231], v[200:203], v[88:91]
	v_mfma_f32_16x16x32_bf16 v[84:87], v[236:239], v[200:203], v[84:87]
	v_mfma_f32_16x16x32_bf16 v[68:71], v[228:231], v[218:221], v[68:71]
	v_mfma_f32_16x16x32_bf16 v[64:67], v[236:239], v[218:221], v[64:67]
	s_setprio 0
	s_mov_b32 m0, s29
	v_lshl_add_u64 v[210:211], s[20:21], 0, v[162:163]
	s_barrier
	ds_read_b128 v[148:151], v198 offset:16384
	ds_read_b128 v[152:155], v198 offset:17408
	ds_read_b128 v[184:187], v198 offset:18432
	ds_read_b128 v[188:191], v198 offset:19456
	ds_read_b128 v[192:195], v198 offset:20480
	ds_read_b128 v[200:203], v198 offset:21504
	ds_read_b128 v[204:207], v198 offset:22528
	ds_read_b128 v[218:221], v198 offset:23552
	global_load_lds_dwordx4 v[210:211], off
	v_lshl_add_u64 v[240:241], s[20:21], 0, v[158:159]
	s_mov_b32 m0, s30
	s_nop 0
	global_load_lds_dwordx4 v[240:241], off
	s_barrier
	s_waitcnt lgkmcnt(0)
	s_setprio 1
	s_waitcnt lgkmcnt(0)
	v_mfma_f32_16x16x32_bf16 v[60:63], v[132:135], v[148:151], v[60:63]
	v_mfma_f32_16x16x32_bf16 v[56:59], v[140:143], v[148:151], v[56:59]
	v_mfma_f32_16x16x32_bf16 v[44:47], v[132:135], v[184:187], v[44:47]
	v_mfma_f32_16x16x32_bf16 v[40:43], v[140:143], v[184:187], v[40:43]
	v_mfma_f32_16x16x32_bf16 v[28:31], v[132:135], v[192:195], v[28:31]
	v_mfma_f32_16x16x32_bf16 v[24:27], v[140:143], v[192:195], v[24:27]
	v_mfma_f32_16x16x32_bf16 v[12:15], v[132:135], v[204:207], v[12:15]
	v_mfma_f32_16x16x32_bf16 v[8:11], v[140:143], v[204:207], v[8:11]
	v_mfma_f32_16x16x32_bf16 v[60:63], v[136:139], v[152:155], v[60:63]
	v_mfma_f32_16x16x32_bf16 v[56:59], v[144:147], v[152:155], v[56:59]
	v_mfma_f32_16x16x32_bf16 v[44:47], v[136:139], v[188:191], v[44:47]
	v_mfma_f32_16x16x32_bf16 v[40:43], v[144:147], v[188:191], v[40:43]
	v_mfma_f32_16x16x32_bf16 v[28:31], v[136:139], v[200:203], v[28:31]
	v_mfma_f32_16x16x32_bf16 v[24:27], v[144:147], v[200:203], v[24:27]
	v_mfma_f32_16x16x32_bf16 v[12:15], v[136:139], v[218:221], v[12:15]
	v_mfma_f32_16x16x32_bf16 v[8:11], v[144:147], v[218:221], v[8:11]
	s_setprio 0
	s_barrier
	s_add_u32 s22, s22, s6
	s_addc_u32 s23, s23, s7
	s_add_i32 s47, s48, s28
	v_lshl_add_u64 v[242:243], s[22:23], 0, v[160:161]
	s_mov_b32 m0, s47
	v_lshl_add_u64 v[244:245], s[22:23], 0, v[156:157]
	global_load_lds_dwordx4 v[242:243], off
	s_add_i32 m0, s47, 0x2000
	s_nop 0
	global_load_lds_dwordx4 v[244:245], off
	s_waitcnt vmcnt(10)
	s_barrier
	s_setprio 1
	v_mfma_f32_16x16x32_bf16 v[52:55], v[224:227], v[148:151], v[52:55]
	v_mfma_f32_16x16x32_bf16 v[48:51], v[232:235], v[148:151], v[48:51]
	v_mfma_f32_16x16x32_bf16 v[36:39], v[224:227], v[184:187], v[36:39]
	v_mfma_f32_16x16x32_bf16 v[32:35], v[232:235], v[184:187], v[32:35]
	v_mfma_f32_16x16x32_bf16 v[20:23], v[224:227], v[192:195], v[20:23]
	v_mfma_f32_16x16x32_bf16 v[16:19], v[232:235], v[192:195], v[16:19]
	v_mfma_f32_16x16x32_bf16 v[4:7], v[224:227], v[204:207], v[4:7]
	v_mfma_f32_16x16x32_bf16 v[0:3], v[232:235], v[204:207], v[0:3]
	v_mfma_f32_16x16x32_bf16 v[52:55], v[228:231], v[152:155], v[52:55]
	v_mfma_f32_16x16x32_bf16 v[48:51], v[236:239], v[152:155], v[48:51]
	v_mfma_f32_16x16x32_bf16 v[36:39], v[228:231], v[188:191], v[36:39]
	v_mfma_f32_16x16x32_bf16 v[32:35], v[236:239], v[188:191], v[32:35]
	v_mfma_f32_16x16x32_bf16 v[20:23], v[228:231], v[200:203], v[20:23]
	v_mfma_f32_16x16x32_bf16 v[16:19], v[236:239], v[200:203], v[16:19]
	v_mfma_f32_16x16x32_bf16 v[4:7], v[228:231], v[218:221], v[4:7]
	v_mfma_f32_16x16x32_bf16 v[0:3], v[236:239], v[218:221], v[0:3]
	s_setprio 0
	s_add_i32 s22, 0, 0x18000
	v_add_u32_e32 v144, s22, v196
	s_barrier
	ds_read_b128 v[132:135], v144
	ds_read_b128 v[136:139], v144 offset:1024
	ds_read_b128 v[140:143], v144 offset:2048
	ds_read_b128 v[144:147], v144 offset:3072
	s_add_u32 s20, s20, s6
	s_addc_u32 s21, s21, s7
	s_mov_b32 m0, s31
	v_lshl_add_u64 v[224:225], s[20:21], 0, v[162:163]
	ds_read_b128 v[148:151], v198 offset:32768
	ds_read_b128 v[152:155], v198 offset:33792
	ds_read_b128 v[184:187], v198 offset:34816
	ds_read_b128 v[188:191], v198 offset:35840
	ds_read_b128 v[192:195], v198 offset:36864
	ds_read_b128 v[200:203], v198 offset:37888
	ds_read_b128 v[204:207], v198 offset:38912
	ds_read_b128 v[218:221], v198 offset:39936
	global_load_lds_dwordx4 v[224:225], off
	v_lshl_add_u64 v[224:225], s[20:21], 0, v[158:159]
	s_mov_b32 m0, s34
	s_nop 0
	global_load_lds_dwordx4 v[224:225], off
	s_waitcnt lgkmcnt(8)
	s_waitcnt vmcnt(10)
	s_barrier
	s_waitcnt lgkmcnt(0)
	s_setprio 1
	s_waitcnt lgkmcnt(0)
	v_mfma_f32_16x16x32_bf16 v[128:131], v[132:135], v[148:151], v[128:131]
	v_mfma_f32_16x16x32_bf16 v[124:127], v[140:143], v[148:151], v[124:127]
	v_mfma_f32_16x16x32_bf16 v[112:115], v[132:135], v[184:187], v[112:115]
	v_mfma_f32_16x16x32_bf16 v[108:111], v[140:143], v[184:187], v[108:111]
	v_mfma_f32_16x16x32_bf16 v[96:99], v[132:135], v[192:195], v[96:99]
	v_mfma_f32_16x16x32_bf16 v[92:95], v[140:143], v[192:195], v[92:95]
	v_mfma_f32_16x16x32_bf16 v[76:79], v[132:135], v[204:207], v[76:79]
	v_mfma_f32_16x16x32_bf16 v[72:75], v[140:143], v[204:207], v[72:75]
	v_mfma_f32_16x16x32_bf16 v[128:131], v[136:139], v[152:155], v[128:131]
	v_mfma_f32_16x16x32_bf16 v[124:127], v[144:147], v[152:155], v[124:127]
	v_mfma_f32_16x16x32_bf16 v[112:115], v[136:139], v[188:191], v[112:115]
	v_mfma_f32_16x16x32_bf16 v[108:111], v[144:147], v[188:191], v[108:111]
	v_mfma_f32_16x16x32_bf16 v[96:99], v[136:139], v[200:203], v[96:99]
	v_mfma_f32_16x16x32_bf16 v[92:95], v[144:147], v[200:203], v[92:95]
	v_mfma_f32_16x16x32_bf16 v[76:79], v[136:139], v[218:221], v[76:79]
	v_mfma_f32_16x16x32_bf16 v[72:75], v[144:147], v[218:221], v[72:75]
	s_setprio 0
	s_barrier
	s_add_i32 s20, 0, 0x1c000
	s_add_i32 s21, s22, s28
	v_add_u32_e32 v166, s20, v196
	v_lshl_add_u64 v[170:171], v[170:171], 0, s[88:89]
	s_mov_b32 m0, s21
	ds_read_b128 v[224:227], v166
	ds_read_b128 v[228:231], v166 offset:1024
	ds_read_b128 v[232:235], v166 offset:2048
	ds_read_b128 v[236:239], v166 offset:3072
	global_load_lds_dwordx4 v[170:171], off
	v_lshl_add_u64 v[170:171], v[172:173], 0, s[88:89]
	s_add_i32 m0, s21, 0x2000
	s_nop 0
	global_load_lds_dwordx4 v[170:171], off
	s_waitcnt vmcnt(10)
	s_barrier
	s_waitcnt lgkmcnt(0)
	s_setprio 1
	s_waitcnt lgkmcnt(0)
	v_mfma_f32_16x16x32_bf16 v[120:123], v[224:227], v[148:151], v[120:123]
	v_mfma_f32_16x16x32_bf16 v[116:119], v[232:235], v[148:151], v[116:119]
	v_mfma_f32_16x16x32_bf16 v[104:107], v[224:227], v[184:187], v[104:107]
	v_mfma_f32_16x16x32_bf16 v[100:103], v[232:235], v[184:187], v[100:103]
	v_mfma_f32_16x16x32_bf16 v[88:91], v[224:227], v[192:195], v[88:91]
	v_mfma_f32_16x16x32_bf16 v[84:87], v[232:235], v[192:195], v[84:87]
	v_mfma_f32_16x16x32_bf16 v[68:71], v[224:227], v[204:207], v[68:71]
	v_mfma_f32_16x16x32_bf16 v[64:67], v[232:235], v[204:207], v[64:67]
	v_mfma_f32_16x16x32_bf16 v[120:123], v[228:231], v[152:155], v[120:123]
	v_mfma_f32_16x16x32_bf16 v[116:119], v[236:239], v[152:155], v[116:119]
	v_mfma_f32_16x16x32_bf16 v[104:107], v[228:231], v[188:191], v[104:107]
	v_mfma_f32_16x16x32_bf16 v[100:103], v[236:239], v[188:191], v[100:103]
	v_mfma_f32_16x16x32_bf16 v[88:91], v[228:231], v[200:203], v[88:91]
	v_mfma_f32_16x16x32_bf16 v[84:87], v[236:239], v[200:203], v[84:87]
	v_mfma_f32_16x16x32_bf16 v[68:71], v[228:231], v[218:221], v[68:71]
	v_mfma_f32_16x16x32_bf16 v[64:67], v[236:239], v[218:221], v[64:67]
	s_setprio 0
	s_mov_b32 m0, s35
	v_lshl_add_u64 v[170:171], v[210:211], 0, s[88:89]
	s_barrier
	ds_read_b128 v[148:151], v198 offset:49152
	ds_read_b128 v[152:155], v198 offset:50176
	ds_read_b128 v[184:187], v198 offset:51200
	ds_read_b128 v[188:191], v198 offset:52224
	ds_read_b128 v[192:195], v198 offset:53248
	ds_read_b128 v[200:203], v198 offset:54272
	ds_read_b128 v[204:207], v198 offset:55296
	ds_read_b128 v[218:221], v198 offset:56320
	global_load_lds_dwordx4 v[170:171], off
	v_lshl_add_u64 v[170:171], v[240:241], 0, s[88:89]
	s_mov_b32 m0, s36
	s_nop 0
	global_load_lds_dwordx4 v[170:171], off
	s_barrier
	s_waitcnt lgkmcnt(0)
	s_setprio 1
	s_waitcnt lgkmcnt(0)
	v_mfma_f32_16x16x32_bf16 v[60:63], v[132:135], v[148:151], v[60:63]
	v_mfma_f32_16x16x32_bf16 v[56:59], v[140:143], v[148:151], v[56:59]
	v_mfma_f32_16x16x32_bf16 v[44:47], v[132:135], v[184:187], v[44:47]
	v_mfma_f32_16x16x32_bf16 v[40:43], v[140:143], v[184:187], v[40:43]
	v_mfma_f32_16x16x32_bf16 v[28:31], v[132:135], v[192:195], v[28:31]
	v_mfma_f32_16x16x32_bf16 v[24:27], v[140:143], v[192:195], v[24:27]
	v_mfma_f32_16x16x32_bf16 v[12:15], v[132:135], v[204:207], v[12:15]
	v_mfma_f32_16x16x32_bf16 v[8:11], v[140:143], v[204:207], v[8:11]
	v_mfma_f32_16x16x32_bf16 v[60:63], v[136:139], v[152:155], v[60:63]
	v_mfma_f32_16x16x32_bf16 v[56:59], v[144:147], v[152:155], v[56:59]
	v_mfma_f32_16x16x32_bf16 v[44:47], v[136:139], v[188:191], v[44:47]
	v_mfma_f32_16x16x32_bf16 v[40:43], v[144:147], v[188:191], v[40:43]
	v_mfma_f32_16x16x32_bf16 v[28:31], v[136:139], v[200:203], v[28:31]
	v_mfma_f32_16x16x32_bf16 v[24:27], v[144:147], v[200:203], v[24:27]
	v_mfma_f32_16x16x32_bf16 v[12:15], v[136:139], v[218:221], v[12:15]
	v_mfma_f32_16x16x32_bf16 v[8:11], v[144:147], v[218:221], v[8:11]
	s_setprio 0
	s_barrier
	s_add_i32 s20, s20, s28
	v_lshl_add_u64 v[132:133], v[242:243], 0, s[88:89]
	s_mov_b32 m0, s20
	s_nop 0
	global_load_lds_dwordx4 v[132:133], off
	v_lshl_add_u64 v[132:133], v[244:245], 0, s[88:89]
	s_add_i32 m0, s20, 0x2000
	s_nop 0
	global_load_lds_dwordx4 v[132:133], off
	s_waitcnt vmcnt(10)
	s_barrier
	s_setprio 1
	v_mfma_f32_16x16x32_bf16 v[52:55], v[224:227], v[148:151], v[52:55]
	v_mfma_f32_16x16x32_bf16 v[48:51], v[232:235], v[148:151], v[48:51]
	v_mfma_f32_16x16x32_bf16 v[36:39], v[224:227], v[184:187], v[36:39]
	v_mfma_f32_16x16x32_bf16 v[32:35], v[232:235], v[184:187], v[32:35]
	v_mfma_f32_16x16x32_bf16 v[20:23], v[224:227], v[192:195], v[20:23]
	v_mfma_f32_16x16x32_bf16 v[16:19], v[232:235], v[192:195], v[16:19]
	v_mfma_f32_16x16x32_bf16 v[4:7], v[224:227], v[204:207], v[4:7]
	v_mfma_f32_16x16x32_bf16 v[0:3], v[232:235], v[204:207], v[0:3]
	v_mfma_f32_16x16x32_bf16 v[52:55], v[228:231], v[152:155], v[52:55]
	v_mfma_f32_16x16x32_bf16 v[48:51], v[236:239], v[152:155], v[48:51]
	v_mfma_f32_16x16x32_bf16 v[36:39], v[228:231], v[188:191], v[36:39]
	v_mfma_f32_16x16x32_bf16 v[32:35], v[236:239], v[188:191], v[32:35]
	v_mfma_f32_16x16x32_bf16 v[20:23], v[228:231], v[200:203], v[20:23]
	v_mfma_f32_16x16x32_bf16 v[16:19], v[236:239], v[200:203], v[16:19]
	v_mfma_f32_16x16x32_bf16 v[4:7], v[228:231], v[218:221], v[4:7]
	v_mfma_f32_16x16x32_bf16 v[0:3], v[236:239], v[218:221], v[0:3]
	s_setprio 0
	s_add_u32 s44, s44, 0x100
	s_addc_u32 s45, s45, 0
	s_add_u32 s18, s18, 0x100
	s_addc_u32 s19, s19, 0
	s_cmp_ge_i32 s46, s37
	s_mov_b32 s20, s46
	s_barrier
	s_cbranch_scc0 .LBB0_1810
	s_mov_b32 s47, 0x28000
	s_branch .LBB0_1797

.LBB0_1886:
	s_add_i32 s46, s20, 2
	s_add_u32 s22, s18, 0x80
	s_addc_u32 s21, s19, 0
	s_add_i32 s47, 0, 0x10000
	v_add_u32_e32 v144, s47, v147
	ds_read_b128 v[140:143], v144
	ds_read_b128 v[150:153], v144 offset:1024
	ds_read_b128 v[154:157], v144 offset:2048
	ds_read_b128 v[158:161], v144 offset:3072
	s_cmp_eq_u32 s38, s20
	s_cselect_b32 s20, s8, s22
	s_cselect_b32 s21, s9, s21
	s_cselect_b32 s23, s11, s45
	s_cselect_b32 s22, s10, s44
	v_lshl_add_u64 v[144:145], s[18:19], 0, v[138:139]
	s_add_i32 m0, s29, 0xc000
	ds_read_b128 v[162:165], v149
	ds_read_b128 v[176:179], v149 offset:1024
	ds_read_b128 v[180:183], v149 offset:2048
	ds_read_b128 v[184:187], v149 offset:3072
	ds_read_b128 v[188:191], v149 offset:4096
	ds_read_b128 v[192:195], v149 offset:5120
	ds_read_b128 v[196:199], v149 offset:6144
	ds_read_b128 v[200:203], v149 offset:7168
	global_load_lds_dwordx4 v[144:145], off
	v_lshl_add_u64 v[144:145], s[18:19], 0, v[136:137]
	s_add_i32 m0, s29, 0xe000
	s_nop 0
	global_load_lds_dwordx4 v[144:145], off
	s_waitcnt lgkmcnt(8)
	s_waitcnt vmcnt(10)
	s_barrier
	s_waitcnt lgkmcnt(0)
	s_setprio 1
	s_waitcnt lgkmcnt(0)
	v_mfma_f32_16x16x32_bf16 v[128:131], v[140:143], v[162:165], v[128:131]
	v_mfma_f32_16x16x32_bf16 v[124:127], v[154:157], v[162:165], v[124:127]
	v_mfma_f32_16x16x32_bf16 v[112:115], v[140:143], v[180:183], v[112:115]
	v_mfma_f32_16x16x32_bf16 v[108:111], v[154:157], v[180:183], v[108:111]
	v_mfma_f32_16x16x32_bf16 v[96:99], v[140:143], v[188:191], v[96:99]
	v_mfma_f32_16x16x32_bf16 v[92:95], v[154:157], v[188:191], v[92:95]
	v_mfma_f32_16x16x32_bf16 v[76:79], v[140:143], v[196:199], v[76:79]
	v_mfma_f32_16x16x32_bf16 v[72:75], v[154:157], v[196:199], v[72:75]
	v_mfma_f32_16x16x32_bf16 v[128:131], v[150:153], v[176:179], v[128:131]
	v_mfma_f32_16x16x32_bf16 v[124:127], v[158:161], v[176:179], v[124:127]
	v_mfma_f32_16x16x32_bf16 v[112:115], v[150:153], v[184:187], v[112:115]
	v_mfma_f32_16x16x32_bf16 v[108:111], v[158:161], v[184:187], v[108:111]
	v_mfma_f32_16x16x32_bf16 v[96:99], v[150:153], v[192:195], v[96:99]
	v_mfma_f32_16x16x32_bf16 v[92:95], v[158:161], v[192:195], v[92:95]
	v_mfma_f32_16x16x32_bf16 v[76:79], v[150:153], v[200:203], v[76:79]
	v_mfma_f32_16x16x32_bf16 v[72:75], v[158:161], v[200:203], v[72:75]
	s_setprio 0
	s_barrier
	s_add_i32 s48, 0, 0x14000
	v_add_u32_e32 v144, s48, v147
	s_add_i32 s47, s47, s28
	ds_read_b128 v[204:207], v144
	ds_read_b128 v[218:221], v144 offset:1024
	ds_read_b128 v[224:227], v144 offset:2048
	ds_read_b128 v[228:231], v144 offset:3072
	v_lshl_add_u64 v[144:145], s[22:23], 0, v[166:167]
	s_mov_b32 m0, s47
	v_lshl_add_u64 v[170:171], s[22:23], 0, v[134:135]
	global_load_lds_dwordx4 v[144:145], off
	s_add_i32 m0, s47, 0x2000
	s_nop 0
	global_load_lds_dwordx4 v[170:171], off
	s_waitcnt vmcnt(10)
	s_barrier
	s_waitcnt lgkmcnt(0)
	s_setprio 1
	s_waitcnt lgkmcnt(0)
	v_mfma_f32_16x16x32_bf16 v[120:123], v[204:207], v[162:165], v[120:123]
	v_mfma_f32_16x16x32_bf16 v[116:119], v[224:227], v[162:165], v[116:119]
	v_mfma_f32_16x16x32_bf16 v[104:107], v[204:207], v[180:183], v[104:107]
	v_mfma_f32_16x16x32_bf16 v[100:103], v[224:227], v[180:183], v[100:103]
	v_mfma_f32_16x16x32_bf16 v[88:91], v[204:207], v[188:191], v[88:91]
	v_mfma_f32_16x16x32_bf16 v[84:87], v[224:227], v[188:191], v[84:87]
	v_mfma_f32_16x16x32_bf16 v[68:71], v[204:207], v[196:199], v[68:71]
	v_mfma_f32_16x16x32_bf16 v[64:67], v[224:227], v[196:199], v[64:67]
	v_mfma_f32_16x16x32_bf16 v[120:123], v[218:221], v[176:179], v[120:123]
	v_mfma_f32_16x16x32_bf16 v[116:119], v[228:231], v[176:179], v[116:119]
	v_mfma_f32_16x16x32_bf16 v[104:107], v[218:221], v[184:187], v[104:107]
	v_mfma_f32_16x16x32_bf16 v[100:103], v[228:231], v[184:187], v[100:103]
	v_mfma_f32_16x16x32_bf16 v[88:91], v[218:221], v[192:195], v[88:91]
	v_mfma_f32_16x16x32_bf16 v[84:87], v[228:231], v[192:195], v[84:87]
	v_mfma_f32_16x16x32_bf16 v[68:71], v[218:221], v[200:203], v[68:71]
	v_mfma_f32_16x16x32_bf16 v[64:67], v[228:231], v[200:203], v[64:67]
	s_setprio 0
	s_mov_b32 m0, s29
	v_lshl_add_u64 v[172:173], s[20:21], 0, v[166:167]
	s_barrier
	ds_read_b128 v[162:165], v149 offset:16384
	ds_read_b128 v[176:179], v149 offset:17408
	ds_read_b128 v[180:183], v149 offset:18432
	ds_read_b128 v[184:187], v149 offset:19456
	ds_read_b128 v[188:191], v149 offset:20480
	ds_read_b128 v[192:195], v149 offset:21504
	ds_read_b128 v[196:199], v149 offset:22528
	ds_read_b128 v[200:203], v149 offset:23552
	global_load_lds_dwordx4 v[172:173], off
	v_lshl_add_u64 v[210:211], s[20:21], 0, v[134:135]
	s_mov_b32 m0, s30
	s_nop 0
	global_load_lds_dwordx4 v[210:211], off
	s_barrier
	s_waitcnt lgkmcnt(0)
	s_setprio 1
	s_waitcnt lgkmcnt(0)
	v_mfma_f32_16x16x32_bf16 v[60:63], v[140:143], v[162:165], v[60:63]
	v_mfma_f32_16x16x32_bf16 v[56:59], v[154:157], v[162:165], v[56:59]
	v_mfma_f32_16x16x32_bf16 v[44:47], v[140:143], v[180:183], v[44:47]
	v_mfma_f32_16x16x32_bf16 v[40:43], v[154:157], v[180:183], v[40:43]
	v_mfma_f32_16x16x32_bf16 v[28:31], v[140:143], v[188:191], v[28:31]
	v_mfma_f32_16x16x32_bf16 v[24:27], v[154:157], v[188:191], v[24:27]
	v_mfma_f32_16x16x32_bf16 v[12:15], v[140:143], v[196:199], v[12:15]
	v_mfma_f32_16x16x32_bf16 v[8:11], v[154:157], v[196:199], v[8:11]
	v_mfma_f32_16x16x32_bf16 v[60:63], v[150:153], v[176:179], v[60:63]
	v_mfma_f32_16x16x32_bf16 v[56:59], v[158:161], v[176:179], v[56:59]
	v_mfma_f32_16x16x32_bf16 v[44:47], v[150:153], v[184:187], v[44:47]
	v_mfma_f32_16x16x32_bf16 v[40:43], v[158:161], v[184:187], v[40:43]
	v_mfma_f32_16x16x32_bf16 v[28:31], v[150:153], v[192:195], v[28:31]
	v_mfma_f32_16x16x32_bf16 v[24:27], v[158:161], v[192:195], v[24:27]
	v_mfma_f32_16x16x32_bf16 v[12:15], v[150:153], v[200:203], v[12:15]
	v_mfma_f32_16x16x32_bf16 v[8:11], v[158:161], v[200:203], v[8:11]
	s_setprio 0
	s_barrier
	s_add_u32 s22, s22, s12
	s_addc_u32 s23, s23, s13
	s_add_i32 s47, s48, s28
	v_lshl_add_u64 v[232:233], s[22:23], 0, v[166:167]
	s_mov_b32 m0, s47
	v_lshl_add_u64 v[234:235], s[22:23], 0, v[134:135]
	global_load_lds_dwordx4 v[232:233], off
	s_add_i32 m0, s47, 0x2000
	s_nop 0
	global_load_lds_dwordx4 v[234:235], off
	s_waitcnt vmcnt(10)
	s_barrier
	s_setprio 1
	v_mfma_f32_16x16x32_bf16 v[52:55], v[204:207], v[162:165], v[52:55]
	v_mfma_f32_16x16x32_bf16 v[48:51], v[224:227], v[162:165], v[48:51]
	v_mfma_f32_16x16x32_bf16 v[36:39], v[204:207], v[180:183], v[36:39]
	v_mfma_f32_16x16x32_bf16 v[32:35], v[224:227], v[180:183], v[32:35]
	v_mfma_f32_16x16x32_bf16 v[20:23], v[204:207], v[188:191], v[20:23]
	v_mfma_f32_16x16x32_bf16 v[16:19], v[224:227], v[188:191], v[16:19]
	v_mfma_f32_16x16x32_bf16 v[4:7], v[204:207], v[196:199], v[4:7]
	v_mfma_f32_16x16x32_bf16 v[0:3], v[224:227], v[196:199], v[0:3]
	v_mfma_f32_16x16x32_bf16 v[52:55], v[218:221], v[176:179], v[52:55]
	v_mfma_f32_16x16x32_bf16 v[48:51], v[228:231], v[176:179], v[48:51]
	v_mfma_f32_16x16x32_bf16 v[36:39], v[218:221], v[184:187], v[36:39]
	v_mfma_f32_16x16x32_bf16 v[32:35], v[228:231], v[184:187], v[32:35]
	v_mfma_f32_16x16x32_bf16 v[20:23], v[218:221], v[192:195], v[20:23]
	v_mfma_f32_16x16x32_bf16 v[16:19], v[228:231], v[192:195], v[16:19]
	v_mfma_f32_16x16x32_bf16 v[4:7], v[218:221], v[200:203], v[4:7]
	v_mfma_f32_16x16x32_bf16 v[0:3], v[228:231], v[200:203], v[0:3]
	s_setprio 0
	s_add_i32 s22, 0, 0x18000
	v_add_u32_e32 v158, s22, v147
	s_barrier
	ds_read_b128 v[140:143], v158
	ds_read_b128 v[150:153], v158 offset:1024
	ds_read_b128 v[154:157], v158 offset:2048
	ds_read_b128 v[158:161], v158 offset:3072
	s_add_u32 s20, s20, s12
	s_addc_u32 s21, s21, s13
	s_mov_b32 m0, s31
	v_lshl_add_u64 v[204:205], s[20:21], 0, v[166:167]
	ds_read_b128 v[162:165], v149 offset:32768
	ds_read_b128 v[176:179], v149 offset:33792
	ds_read_b128 v[180:183], v149 offset:34816
	ds_read_b128 v[184:187], v149 offset:35840
	ds_read_b128 v[188:191], v149 offset:36864
	ds_read_b128 v[192:195], v149 offset:37888
	ds_read_b128 v[196:199], v149 offset:38912
	ds_read_b128 v[200:203], v149 offset:39936
	global_load_lds_dwordx4 v[204:205], off
	v_lshl_add_u64 v[204:205], s[20:21], 0, v[134:135]
	s_mov_b32 m0, s34
	s_nop 0
	global_load_lds_dwordx4 v[204:205], off
	s_waitcnt lgkmcnt(8)
	s_waitcnt vmcnt(10)
	s_barrier
	s_waitcnt lgkmcnt(0)
	s_setprio 1
	s_waitcnt lgkmcnt(0)
	v_mfma_f32_16x16x32_bf16 v[128:131], v[140:143], v[162:165], v[128:131]
	v_mfma_f32_16x16x32_bf16 v[124:127], v[154:157], v[162:165], v[124:127]
	v_mfma_f32_16x16x32_bf16 v[112:115], v[140:143], v[180:183], v[112:115]
	v_mfma_f32_16x16x32_bf16 v[108:111], v[154:157], v[180:183], v[108:111]
	v_mfma_f32_16x16x32_bf16 v[96:99], v[140:143], v[188:191], v[96:99]
	v_mfma_f32_16x16x32_bf16 v[92:95], v[154:157], v[188:191], v[92:95]
	v_mfma_f32_16x16x32_bf16 v[76:79], v[140:143], v[196:199], v[76:79]
	v_mfma_f32_16x16x32_bf16 v[72:75], v[154:157], v[196:199], v[72:75]
	v_mfma_f32_16x16x32_bf16 v[128:131], v[150:153], v[176:179], v[128:131]
	v_mfma_f32_16x16x32_bf16 v[124:127], v[158:161], v[176:179], v[124:127]
	v_mfma_f32_16x16x32_bf16 v[112:115], v[150:153], v[184:187], v[112:115]
	v_mfma_f32_16x16x32_bf16 v[108:111], v[158:161], v[184:187], v[108:111]
	v_mfma_f32_16x16x32_bf16 v[96:99], v[150:153], v[192:195], v[96:99]
	v_mfma_f32_16x16x32_bf16 v[92:95], v[158:161], v[192:195], v[92:95]
	v_mfma_f32_16x16x32_bf16 v[76:79], v[150:153], v[200:203], v[76:79]
	v_mfma_f32_16x16x32_bf16 v[72:75], v[158:161], v[200:203], v[72:75]
	s_setprio 0
	s_barrier
	s_add_i32 s20, 0, 0x1c000
	s_add_i32 s21, s22, s28
	v_add_u32_e32 v169, s20, v147
	v_lshl_add_u64 v[144:145], v[144:145], 0, s[88:89]
	s_mov_b32 m0, s21
	ds_read_b128 v[204:207], v169
	ds_read_b128 v[218:221], v169 offset:1024
	ds_read_b128 v[224:227], v169 offset:2048
	ds_read_b128 v[228:231], v169 offset:3072
	global_load_lds_dwordx4 v[144:145], off
	v_lshl_add_u64 v[144:145], v[170:171], 0, s[88:89]
	s_add_i32 m0, s21, 0x2000
	s_nop 0
	global_load_lds_dwordx4 v[144:145], off
	s_waitcnt vmcnt(10)
	s_barrier
	s_waitcnt lgkmcnt(0)
	s_setprio 1
	s_waitcnt lgkmcnt(0)
	v_mfma_f32_16x16x32_bf16 v[120:123], v[204:207], v[162:165], v[120:123]
	v_mfma_f32_16x16x32_bf16 v[116:119], v[224:227], v[162:165], v[116:119]
	v_mfma_f32_16x16x32_bf16 v[104:107], v[204:207], v[180:183], v[104:107]
	v_mfma_f32_16x16x32_bf16 v[100:103], v[224:227], v[180:183], v[100:103]
	v_mfma_f32_16x16x32_bf16 v[88:91], v[204:207], v[188:191], v[88:91]
	v_mfma_f32_16x16x32_bf16 v[84:87], v[224:227], v[188:191], v[84:87]
	v_mfma_f32_16x16x32_bf16 v[68:71], v[204:207], v[196:199], v[68:71]
	v_mfma_f32_16x16x32_bf16 v[64:67], v[224:227], v[196:199], v[64:67]
	v_mfma_f32_16x16x32_bf16 v[120:123], v[218:221], v[176:179], v[120:123]
	v_mfma_f32_16x16x32_bf16 v[116:119], v[228:231], v[176:179], v[116:119]
	v_mfma_f32_16x16x32_bf16 v[104:107], v[218:221], v[184:187], v[104:107]
	v_mfma_f32_16x16x32_bf16 v[100:103], v[228:231], v[184:187], v[100:103]
	v_mfma_f32_16x16x32_bf16 v[88:91], v[218:221], v[192:195], v[88:91]
	v_mfma_f32_16x16x32_bf16 v[84:87], v[228:231], v[192:195], v[84:87]
	v_mfma_f32_16x16x32_bf16 v[68:71], v[218:221], v[200:203], v[68:71]
	v_mfma_f32_16x16x32_bf16 v[64:67], v[228:231], v[200:203], v[64:67]
	s_setprio 0
	s_mov_b32 m0, s36
	v_lshl_add_u64 v[144:145], v[172:173], 0, s[88:89]
	s_barrier
	ds_read_b128 v[162:165], v149 offset:49152
	ds_read_b128 v[176:179], v149 offset:50176
	ds_read_b128 v[180:183], v149 offset:51200
	ds_read_b128 v[184:187], v149 offset:52224
	ds_read_b128 v[188:191], v149 offset:53248
	ds_read_b128 v[192:195], v149 offset:54272
	ds_read_b128 v[196:199], v149 offset:55296
	ds_read_b128 v[200:203], v149 offset:56320
	global_load_lds_dwordx4 v[144:145], off
	v_lshl_add_u64 v[144:145], v[210:211], 0, s[88:89]
	s_mov_b32 m0, s37
	s_nop 0
	global_load_lds_dwordx4 v[144:145], off
	s_barrier
	s_waitcnt lgkmcnt(0)
	s_setprio 1
	s_waitcnt lgkmcnt(0)
	v_mfma_f32_16x16x32_bf16 v[60:63], v[140:143], v[162:165], v[60:63]
	v_mfma_f32_16x16x32_bf16 v[56:59], v[154:157], v[162:165], v[56:59]
	v_mfma_f32_16x16x32_bf16 v[44:47], v[140:143], v[180:183], v[44:47]
	v_mfma_f32_16x16x32_bf16 v[40:43], v[154:157], v[180:183], v[40:43]
	v_mfma_f32_16x16x32_bf16 v[28:31], v[140:143], v[188:191], v[28:31]
	v_mfma_f32_16x16x32_bf16 v[24:27], v[154:157], v[188:191], v[24:27]
	v_mfma_f32_16x16x32_bf16 v[12:15], v[140:143], v[196:199], v[12:15]
	v_mfma_f32_16x16x32_bf16 v[8:11], v[154:157], v[196:199], v[8:11]
	v_mfma_f32_16x16x32_bf16 v[60:63], v[150:153], v[176:179], v[60:63]
	v_mfma_f32_16x16x32_bf16 v[56:59], v[158:161], v[176:179], v[56:59]
	v_mfma_f32_16x16x32_bf16 v[44:47], v[150:153], v[184:187], v[44:47]
	v_mfma_f32_16x16x32_bf16 v[40:43], v[158:161], v[184:187], v[40:43]
	v_mfma_f32_16x16x32_bf16 v[28:31], v[150:153], v[192:195], v[28:31]
	v_mfma_f32_16x16x32_bf16 v[24:27], v[158:161], v[192:195], v[24:27]
	v_mfma_f32_16x16x32_bf16 v[12:15], v[150:153], v[200:203], v[12:15]
	v_mfma_f32_16x16x32_bf16 v[8:11], v[158:161], v[200:203], v[8:11]
	s_setprio 0
	s_barrier
	s_add_i32 s20, s20, s28
	v_lshl_add_u64 v[140:141], v[232:233], 0, s[88:89]
	s_mov_b32 m0, s20
	s_nop 0
	global_load_lds_dwordx4 v[140:141], off
	v_lshl_add_u64 v[140:141], v[234:235], 0, s[88:89]
	s_add_i32 m0, s20, 0x2000
	s_nop 0
	global_load_lds_dwordx4 v[140:141], off
	s_waitcnt vmcnt(10)
	s_barrier
	s_setprio 1
	v_mfma_f32_16x16x32_bf16 v[52:55], v[204:207], v[162:165], v[52:55]
	v_mfma_f32_16x16x32_bf16 v[48:51], v[224:227], v[162:165], v[48:51]
	v_mfma_f32_16x16x32_bf16 v[36:39], v[204:207], v[180:183], v[36:39]
	v_mfma_f32_16x16x32_bf16 v[32:35], v[224:227], v[180:183], v[32:35]
	v_mfma_f32_16x16x32_bf16 v[20:23], v[204:207], v[188:191], v[20:23]
	v_mfma_f32_16x16x32_bf16 v[16:19], v[224:227], v[188:191], v[16:19]
	v_mfma_f32_16x16x32_bf16 v[4:7], v[204:207], v[196:199], v[4:7]
	v_mfma_f32_16x16x32_bf16 v[0:3], v[224:227], v[196:199], v[0:3]
	v_mfma_f32_16x16x32_bf16 v[52:55], v[218:221], v[176:179], v[52:55]
	v_mfma_f32_16x16x32_bf16 v[48:51], v[228:231], v[176:179], v[48:51]
	v_mfma_f32_16x16x32_bf16 v[36:39], v[218:221], v[184:187], v[36:39]
	v_mfma_f32_16x16x32_bf16 v[32:35], v[228:231], v[184:187], v[32:35]
	v_mfma_f32_16x16x32_bf16 v[20:23], v[218:221], v[192:195], v[20:23]
	v_mfma_f32_16x16x32_bf16 v[16:19], v[228:231], v[192:195], v[16:19]
	v_mfma_f32_16x16x32_bf16 v[4:7], v[218:221], v[200:203], v[4:7]
	v_mfma_f32_16x16x32_bf16 v[0:3], v[228:231], v[200:203], v[0:3]
	s_setprio 0
	s_add_u32 s44, s44, 0x100
	s_addc_u32 s45, s45, 0
	s_add_u32 s18, s18, 0x100
	s_addc_u32 s19, s19, 0
	s_cmp_ge_i32 s46, s35
	s_mov_b32 s20, s46
	s_barrier
	s_cbranch_scc0 .LBB0_1886
	s_mov_b32 s47, 0x28000
	s_branch .LBB0_1873
